# delta recurrence: KDT rows stored permuted so producer ds_write_b16 are bank-conflict free (reads take 4-way conflicts on the slack side)
# baseline (speedup 1.0000x reference)
; #define LAS __attribute__((address_space(3)))
; __device__ __forceinline__ unsigned f2bf(float f) { return pk2(f, f) & 0xffffu; }
; __device__ __forceinline__ void unpack8(const u32x4 u, float* x) { x[0] = bflo(u.x); x[1] = bfhi(u.x); x[2] = bflo(u.y); x[3] = bfhi(u.y); x[4] = bflo(u.z); x[5] = bfhi(u.z); x[6] = bflo(u.w); x[7] = bfhi(u.w); }
; __device__ __forceinline__ int perm16(int e) { return (e & ~12) | ((e >> 1) & 4) | ((e << 1) & 8); }
; __device__ __forceinline__ void delta_rec_stage(LAS unsigned char* buf, int pt, const DeltaPre& dp) {
;     const int tt = pt >> 3, dg = pt & 7, d0 = dg * 16;
;     { LAS bf16* dst = (LAS bf16*)(buf + (pt < 128 ? DR_TI : DR_AT)) + ((pt & 127) >> 2) * 40 + (pt & 3) * 8; *(LAS u32x4*)dst = dp.tia; }
;     if (pt == 0) *(LAS float*)(buf + DR_EGL) = __expf(dp.gl);
;     const float eg = __expf(dp.gct), ekd = __expf(dp.gl - dp.gct);
;     const float fq = dp.nq * eg, fkb = dp.nk * dp.bet * eg, fkd = dp.nk * ekd, bet = dp.bet;
;     float k[16], q[16], v[16];
;     unpack8(dp.k0, k); unpack8(dp.k1, k + 8); unpack8(dp.q0, q); unpack8(dp.q1, q + 8); unpack8(dp.v0, v); unpack8(dp.v1, v + 8);
;     LAS bf16* KB = (LAS bf16*)(buf + DR_KB) + tt * 136 + d0; LAS bf16* QD = (LAS bf16*)(buf + DR_QD) + tt * 136 + d0;
;     *(LAS bf16x8*)KB = pack8(k[0] * fkb, k[1] * fkb, k[2] * fkb, k[3] * fkb, k[8] * fkb, k[9] * fkb, k[10] * fkb, k[11] * fkb);
;     *(LAS bf16x8*)(KB + 8) = pack8(k[4] * fkb, k[5] * fkb, k[6] * fkb, k[7] * fkb, k[12] * fkb, k[13] * fkb, k[14] * fkb, k[15] * fkb);
;     *(LAS bf16x8*)QD = pack8(q[0] * fq, q[1] * fq, q[2] * fq, q[3] * fq, q[8] * fq, q[9] * fq, q[10] * fq, q[11] * fq);
;     *(LAS bf16x8*)(QD + 8) = pack8(q[4] * fq, q[5] * fq, q[6] * fq, q[7] * fq, q[12] * fq, q[13] * fq, q[14] * fq, q[15] * fq);
;     LAS bf16* KDT = (LAS bf16*)(buf + DR_KDT) + d0 * 40 + perm16(tt);
; #pragma unroll
;     for (int e = 0; e < 16; ++e) KDT[e * 40] = (bf16)f2bf(k[e] * fkd);
;     LAS float* VB = (LAS float*)(buf + DR_VB) + tt * 132 + d0;
; #pragma unroll
;     for (int e4 = 0; e4 < 4; ++e4) *(LAS f32x4*)(VB + 4 * e4) = (f32x4){v[4 * e4] * bet, v[4 * e4 + 1] * bet, v[4 * e4 + 2] * bet, v[4 * e4 + 3] * bet};
; }
.LBB0_1815:
	s_or_b64 exec, exec, s[6:7]
	v_mul_f32_e32 v25, 0x3fb8aa3b, v29
	v_sub_f32_e32 v29, v30, v29
	v_mul_f32_e32 v29, 0x3fb8aa3b, v29
	v_exp_f32_e32 v25, v25
	v_exp_f32_e32 v29, v29
	v_mul_f32_e32 v30, v26, v31
	s_movk_i32 s3, 0x110
	v_mul_f32_e32 v34, v25, v32
	v_mul_f32_e32 v36, v25, v30
	v_mul_f32_e32 v25, v29, v31
	v_mul_lo_u32 v29, v24, s3
	v_lshlrev_b32_e32 v38, 16, v20
	v_and_b32_e32 v39, 0xffff0000, v20
	v_lshlrev_b32_e32 v20, 16, v21
	v_and_b32_e32 v21, 0xffff0000, v21
	v_lshlrev_b32_e32 v40, 16, v16
	v_and_b32_e32 v41, 0xffff0000, v16
	v_lshlrev_b32_e32 v44, 16, v17
	v_and_b32_e32 v45, 0xffff0000, v17
	v_add_u32_e32 v29, 0, v29
	v_pk_mul_f32 v[30:31], v[36:37], v[38:39] op_sel_hi:[0,1]
	v_pk_mul_f32 v[32:33], v[36:37], v[20:21] op_sel_hi:[0,1]
	v_pk_mul_f32 v[42:43], v[36:37], v[40:41] op_sel_hi:[0,1]
	v_pk_mul_f32 v[16:17], v[36:37], v[44:45] op_sel_hi:[0,1]
	v_lshl_add_u32 v35, v28, 1, v29
	v_cvt_pk_bf16_f32 v30, v30, v31
	v_cvt_pk_bf16_f32 v31, v32, v33
	v_cvt_pk_bf16_f32 v32, v42, v43
	v_cvt_pk_bf16_f32 v33, v16, v17
	ds_write_b128 v35, v[30:33]
	v_lshlrev_b32_e32 v30, 16, v22
	v_and_b32_e32 v31, 0xffff0000, v22
	v_lshlrev_b32_e32 v22, 16, v23
	v_and_b32_e32 v23, 0xffff0000, v23
	v_lshlrev_b32_e32 v42, 16, v18
	v_and_b32_e32 v43, 0xffff0000, v18
	v_lshlrev_b32_e32 v48, 16, v19
	v_and_b32_e32 v49, 0xffff0000, v19
	v_pk_mul_f32 v[16:17], v[36:37], v[30:31] op_sel_hi:[0,1]
	v_pk_mul_f32 v[32:33], v[36:37], v[22:23] op_sel_hi:[0,1]
	v_pk_mul_f32 v[46:47], v[36:37], v[42:43] op_sel_hi:[0,1]
	v_pk_mul_f32 v[36:37], v[36:37], v[48:49] op_sel_hi:[0,1]
	v_cvt_pk_bf16_f32 v16, v16, v17
	v_cvt_pk_bf16_f32 v17, v32, v33
	v_cvt_pk_bf16_f32 v18, v46, v47
	v_cvt_pk_bf16_f32 v19, v36, v37
	ds_write_b128 v35, v[16:19] offset:16
	v_lshlrev_b32_e32 v16, 16, v12
	v_and_b32_e32 v17, 0xffff0000, v12
	v_lshlrev_b32_e32 v12, 16, v13
	v_and_b32_e32 v13, 0xffff0000, v13
	v_lshlrev_b32_e32 v18, 16, v8
	v_and_b32_e32 v19, 0xffff0000, v8
	v_lshlrev_b32_e32 v8, 16, v9
	v_and_b32_e32 v9, 0xffff0000, v9
	v_pk_mul_f32 v[16:17], v[34:35], v[16:17] op_sel_hi:[0,1]
	v_pk_mul_f32 v[12:13], v[34:35], v[12:13] op_sel_hi:[0,1]
	v_pk_mul_f32 v[18:19], v[34:35], v[18:19] op_sel_hi:[0,1]
	v_pk_mul_f32 v[8:9], v[34:35], v[8:9] op_sel_hi:[0,1]
	v_cvt_pk_bf16_f32 v16, v16, v17
	v_cvt_pk_bf16_f32 v17, v12, v13
	v_cvt_pk_bf16_f32 v18, v18, v19
	v_cvt_pk_bf16_f32 v19, v8, v9
	v_lshlrev_b32_e32 v8, 16, v14
	v_and_b32_e32 v9, 0xffff0000, v14
	v_lshlrev_b32_e32 v12, 16, v15
	v_and_b32_e32 v13, 0xffff0000, v15
	v_lshlrev_b32_e32 v14, 16, v10
	v_and_b32_e32 v15, 0xffff0000, v10
	v_lshlrev_b32_e32 v10, 16, v11
	v_and_b32_e32 v11, 0xffff0000, v11
	ds_write_b128 v35, v[16:19] offset:8704
	v_pk_mul_f32 v[8:9], v[34:35], v[8:9] op_sel_hi:[0,1]
	v_pk_mul_f32 v[12:13], v[34:35], v[12:13] op_sel_hi:[0,1]
	v_pk_mul_f32 v[14:15], v[34:35], v[14:15] op_sel_hi:[0,1]
	v_pk_mul_f32 v[16:17], v[34:35], v[10:11] op_sel_hi:[0,1]
	v_cvt_pk_bf16_f32 v8, v8, v9
	v_cvt_pk_bf16_f32 v9, v12, v13
	v_cvt_pk_bf16_f32 v10, v14, v15
	v_cvt_pk_bf16_f32 v11, v16, v17
	ds_write_b128 v35, v[8:11] offset:8720
	v_lshrrev_b32_e32 v10, 3, v113
	v_mul_u32_u24_e32 v8, 5, v28
	v_and_b32_e32 v10, 8, v10
	v_and_b32_e32 v9, 0x1ffffff3, v24
	v_add3_u32 v8, 0, v8, v10
	v_lshlrev_b32_e32 v10, 2, v24
	v_lshlrev_b32_e32 v9, 1, v9
	v_and_b32_e32 v10, 16, v10
	v_add3_u32 v8, v8, v9, v10
	v_mul_f32_e32 v9, v25, v38
	v_cvt_pk_bf16_f32 v9, v9, s0
	ds_write_b16 v8, v9 offset:17408
	v_mul_f32_e32 v9, v25, v39
	v_cvt_pk_bf16_f32 v9, v9, s0
	ds_write_b16 v8, v9 offset:18048
	v_mul_f32_e32 v9, v25, v20
	v_cvt_pk_bf16_f32 v9, v9, s0
	ds_write_b16 v8, v9 offset:18688
	v_mul_f32_e32 v9, v25, v21
	v_cvt_pk_bf16_f32 v9, v9, s0
	ds_write_b16 v8, v9 offset:19328
	v_mul_f32_e32 v9, v25, v30
	v_cvt_pk_bf16_f32 v9, v9, s0
	ds_write_b16 v8, v9 offset:19968
	v_mul_f32_e32 v9, v25, v31
	v_cvt_pk_bf16_f32 v9, v9, s0
	ds_write_b16 v8, v9 offset:20608
	v_mul_f32_e32 v9, v25, v22
	v_cvt_pk_bf16_f32 v9, v9, s0
	ds_write_b16 v8, v9 offset:21248
	v_mul_f32_e32 v9, v25, v23
	v_cvt_pk_bf16_f32 v9, v9, s0
	ds_write_b16 v8, v9 offset:21888
	v_mul_f32_e32 v9, v25, v40
	v_cvt_pk_bf16_f32 v9, v9, s0
	ds_write_b16 v8, v9 offset:22528
	v_mul_f32_e32 v9, v25, v41
	v_cvt_pk_bf16_f32 v9, v9, s0
	ds_write_b16 v8, v9 offset:23168
	v_mul_f32_e32 v9, v25, v44
	v_cvt_pk_bf16_f32 v9, v9, s0
	ds_write_b16 v8, v9 offset:23808
	v_mul_f32_e32 v9, v25, v45
	v_cvt_pk_bf16_f32 v9, v9, s0
	ds_write_b16 v8, v9 offset:24448
	v_mul_f32_e32 v9, v25, v42
	v_cvt_pk_bf16_f32 v9, v9, s0
	ds_write_b16 v8, v9 offset:25088
	v_mul_f32_e32 v9, v25, v43
	v_cvt_pk_bf16_f32 v9, v9, s0
	ds_write_b16 v8, v9 offset:25728
	v_mul_f32_e32 v9, v25, v48
	v_cvt_pk_bf16_f32 v9, v9, s0
	ds_write_b16 v8, v9 offset:26368
	v_mul_f32_e32 v9, v25, v49
	v_cvt_pk_bf16_f32 v9, v9, s0
	ds_write_b16 v8, v9 offset:27008
	v_lshlrev_b32_e32 v8, 8, v24
	v_lshlrev_b32_e32 v9, 2, v28
	v_add3_u32 v12, v29, v8, v9
	v_lshlrev_b32_e32 v8, 16, v4
	v_and_b32_e32 v9, 0xffff0000, v4
	v_lshlrev_b32_e32 v4, 16, v5
	v_and_b32_e32 v5, 0xffff0000, v5
	v_pk_mul_f32 v[10:11], v[26:27], v[4:5] op_sel_hi:[0,1]
	v_lshlrev_b32_e32 v4, 16, v6
	v_and_b32_e32 v5, 0xffff0000, v6
	v_lshlrev_b32_e32 v6, 16, v7
	v_and_b32_e32 v7, 0xffff0000, v7
	v_pk_mul_f32 v[4:5], v[26:27], v[4:5] op_sel_hi:[0,1]
	v_pk_mul_f32 v[6:7], v[26:27], v[6:7] op_sel_hi:[0,1]
	ds_write_b128 v12, v[4:7] offset:32784
	v_lshlrev_b32_e32 v4, 16, v0
	v_and_b32_e32 v5, 0xffff0000, v0
	v_lshlrev_b32_e32 v0, 16, v1
	v_and_b32_e32 v1, 0xffff0000, v1
	v_pk_mul_f32 v[6:7], v[26:27], v[0:1] op_sel_hi:[0,1]
	v_lshlrev_b32_e32 v0, 16, v2
	v_and_b32_e32 v1, 0xffff0000, v2
	v_lshlrev_b32_e32 v2, 16, v3
	v_and_b32_e32 v3, 0xffff0000, v3
	v_pk_mul_f32 v[8:9], v[26:27], v[8:9] op_sel_hi:[0,1]
	v_pk_mul_f32 v[4:5], v[26:27], v[4:5] op_sel_hi:[0,1]
	v_pk_mul_f32 v[0:1], v[26:27], v[0:1] op_sel_hi:[0,1]
	v_pk_mul_f32 v[2:3], v[26:27], v[2:3] op_sel_hi:[0,1]
	ds_write_b128 v12, v[8:11] offset:32768
	ds_write_b128 v12, v[4:7] offset:32800
	ds_write_b128 v12, v[0:3] offset:32816

; __device__ __forceinline__ void delta_rec_task(const Params& P, LAS unsigned char* lds, int b, int h, int tid) {
;     ...
;         const int lane = opq(tid) & 63, n = lane & 31, hh = lane >> 5;
;         for (int c = 0; c < NC; ++c) {
;             LAS unsigned char* buf = lds + (c & 1) * DR_BUF;
;             const int vb = wave;
;             bf16x8 SB[8];
; #pragma unroll
;             for (int s = 0; s < 8; ++s) { const int kb = s >> 1, o = 8 * (s & 1); SB[s] = pack8(S[kb][o], S[kb][o + 1], S[kb][o + 2], S[kb][o + 3], S[kb][o + 4], S[kb][o + 5], S[kb][o + 6], S[kb][o + 7]); }
;             f32x16 X1, P1;
; #pragma unroll
;             for (int r = 0; r < 16; ++r) { X1[r] = 0.f; P1[r] = 0.f; }
;             const LAS bf16* KB = (const LAS bf16*)(buf + DR_KB) + n * 136 + 8 * hh; const LAS bf16* QD = (const LAS bf16*)(buf + DR_QD) + n * 136 + 8 * hh;
; #pragma unroll
;             for (int s = 0; s < 8; ++s) { X1 = __builtin_amdgcn_mfma_f32_32x32x16_bf16(*(const LAS bf16x8*)(KB + 16 * s), SB[s], X1, 0, 0, 0);
;                 P1 = __builtin_amdgcn_mfma_f32_32x32x16_bf16(*(const LAS bf16x8*)(QD + 16 * s), SB[s], P1, 0, 0, 0); }
;             const LAS float* VB = (const LAS float*)(buf + DR_VB) + 32 * vb + n;
;             float Y[16];
; #pragma unroll
;             for (int r = 0; r < 16; ++r) Y[r] = VB[((r & 3) + 8 * (r >> 2) + 4 * hh) * 132] - X1[r];
;             const bf16x8 YB0 = pack8(Y[0], Y[1], Y[2], Y[3], Y[4], Y[5], Y[6], Y[7]), YB1 = pack8(Y[8], Y[9], Y[10], Y[11], Y[12], Y[13], Y[14], Y[15]);
;             f32x16 VN;
; #pragma unroll
;             for (int r = 0; r < 16; ++r) VN[r] = 0.f;
;             const LAS bf16* TI = (const LAS bf16*)(buf + DR_TI) + n * 40 + 8 * hh; const LAS bf16* AT = (const LAS bf16*)(buf + DR_AT) + n * 40 + 8 * hh;
;             VN = __builtin_amdgcn_mfma_f32_32x32x16_bf16(*(const LAS bf16x8*)TI, YB0, VN, 0, 0, 0);
;             VN = __builtin_amdgcn_mfma_f32_32x32x16_bf16(*(const LAS bf16x8*)(TI + 16), YB1, VN, 0, 0, 0);
;             const bf16x8 VB0 = pack8(VN[0], VN[1], VN[2], VN[3], VN[4], VN[5], VN[6], VN[7]), VB1 = pack8(VN[8], VN[9], VN[10], VN[11], VN[12], VN[13], VN[14], VN[15]);
;             P1 = __builtin_amdgcn_mfma_f32_32x32x16_bf16(*(const LAS bf16x8*)AT, VB0, P1, 0, 0, 0);
;             P1 = __builtin_amdgcn_mfma_f32_32x32x16_bf16(*(const LAS bf16x8*)(AT + 16), VB1, P1, 0, 0, 0);
.LBB0_1832:
	v_mov_b32_e32 v0, v113
	s_add_i32 s5, 0, 0x18420
	v_and_b32_e32 v1, 31, v0
	v_and_b32_e32 v175, 15, v1
	v_lshrrev_b32_e32 v176, 4, v1
	v_lshl_add_u32 v175, v175, 3, v176
	v_mul_u32_u24_e32 v175, 0x50, v175
	v_bfe_u32 v0, v0, 5, 1
	s_movk_i32 s4, 0x840
	v_mov_b32_e32 v5, s5
	v_mul_u32_u24_e32 v2, 0x88, v1
	v_lshlrev_b32_e32 v3, 3, v0
	v_mul_u32_u24_e32 v4, 40, v1
	v_mul_u32_u24_e32 v114, 0x840, v0
	v_mad_u32_u24 v0, v0, s4, v5
	v_lshlrev_b32_e32 v5, 7, v27
	v_lshlrev_b32_e32 v115, 2, v1
	v_mov_b32_e32 v48, 0
	s_mov_b32 s3, 0
	v_add3_u32 v116, v0, v5, v115
	s_waitcnt vmcnt(5)
	v_lshlrev_b32_e32 v117, 1, v2
	s_waitcnt vmcnt(4)
	v_lshlrev_b32_e32 v118, 1, v3
	s_waitcnt vmcnt(2)
	v_lshlrev_b32_e32 v119, 1, v4
	v_mov_b32_e32 v49, v48
	v_mov_b32_e32 v50, v48
	v_mov_b32_e32 v51, v48
	v_mov_b32_e32 v52, v48
	v_mov_b32_e32 v53, v48
	v_mov_b32_e32 v54, v48
	v_mov_b32_e32 v55, v48
	v_mov_b32_e32 v56, v48
	v_mov_b32_e32 v57, v48
	v_mov_b32_e32 v58, v48
	v_mov_b32_e32 v59, v48
	v_mov_b32_e32 v60, v48
	v_mov_b32_e32 v61, v48
	v_mov_b32_e32 v62, v48
	v_mov_b32_e32 v63, v48
	v_mov_b32_e32 v32, v48
	v_mov_b32_e32 v33, v48
	v_mov_b32_e32 v34, v48
	v_mov_b32_e32 v35, v48
	v_mov_b32_e32 v36, v48
	v_mov_b32_e32 v37, v48
	v_mov_b32_e32 v38, v48
	v_mov_b32_e32 v39, v48
	v_mov_b32_e32 v40, v48
	v_mov_b32_e32 v41, v48
	v_mov_b32_e32 v42, v48
	v_mov_b32_e32 v43, v48
	v_mov_b32_e32 v44, v48
	v_mov_b32_e32 v45, v48
	v_mov_b32_e32 v46, v48
	v_mov_b32_e32 v47, v48
	v_mov_b32_e32 v16, v48
	v_mov_b32_e32 v17, v48
	v_mov_b32_e32 v18, v48
	v_mov_b32_e32 v19, v48
	v_mov_b32_e32 v20, v48
	v_mov_b32_e32 v21, v48
	v_mov_b32_e32 v22, v48
	v_mov_b32_e32 v23, v48
	v_mov_b32_e32 v24, v48
	v_mov_b32_e32 v25, v48
	v_mov_b32_e32 v26, v48
	v_mov_b32_e32 v27, v48
	v_mov_b32_e32 v28, v48
	v_mov_b32_e32 v29, v48
	v_mov_b32_e32 v30, v48
	v_mov_b32_e32 v31, v48
	v_mov_b32_e32 v0, v48
	v_mov_b32_e32 v1, v48
	v_mov_b32_e32 v2, v48
	v_mov_b32_e32 v3, v48
	v_mov_b32_e32 v4, v48
	v_mov_b32_e32 v5, v48
	v_mov_b32_e32 v6, v48
	v_mov_b32_e32 v7, v48
	v_mov_b32_e32 v8, v48
	v_mov_b32_e32 v9, v48
	v_mov_b32_e32 v10, v48
	v_mov_b32_e32 v11, v48
	v_mov_b32_e32 v12, v48
	v_mov_b32_e32 v13, v48
	v_mov_b32_e32 v14, v48
	v_mov_b32_e32 v15, v48
.LBB0_1833:
	s_and_b32 s4, s3, 1
	s_mul_i32 s5, s4, 0xc210
	s_add_i32 s5, s5, 0
	v_add3_u32 v136, s5, v117, v118
	ds_read_b128 v[64:67], v136
	ds_read_b128 v[96:99], v136 offset:32
	v_cvt_pk_bf16_f32 v80, v48, v49
	v_cvt_pk_bf16_f32 v81, v50, v51
	v_cvt_pk_bf16_f32 v82, v52, v53
	v_cvt_pk_bf16_f32 v83, v54, v55
	ds_read_b128 v[84:87], v136 offset:8704
	ds_read_b128 v[100:103], v136 offset:8736
	s_waitcnt lgkmcnt(3)
	v_mfma_f32_32x32x16_bf16 v[64:79], v[64:67], v[80:83], 0
	v_cvt_pk_bf16_f32 v104, v56, v57
	v_cvt_pk_bf16_f32 v105, v58, v59
	v_cvt_pk_bf16_f32 v106, v60, v61
	v_cvt_pk_bf16_f32 v107, v62, v63
	v_cvt_pk_bf16_f32 v108, v32, v33
	v_cvt_pk_bf16_f32 v109, v34, v35
	v_cvt_pk_bf16_f32 v110, v36, v37
	s_waitcnt vmcnt(0) lgkmcnt(1)
	v_mfma_f32_32x32x16_bf16 v[80:95], v[84:87], v[80:83], 0
	v_cvt_pk_bf16_f32 v111, v38, v39
	v_cvt_pk_bf16_f32 v120, v16, v17
	v_cvt_pk_bf16_f32 v121, v18, v19
	v_cvt_pk_bf16_f32 v122, v20, v21
	v_cvt_pk_bf16_f32 v123, v22, v23
	v_lshl_add_u32 v137, v112, 2, s5
	v_add3_u32 v162, v137, v115, v114
	v_mfma_f32_32x32x16_bf16 v[64:79], v[96:99], v[104:107], v[64:79]
	v_cvt_pk_bf16_f32 v96, v40, v41
	v_cvt_pk_bf16_f32 v97, v42, v43
	v_cvt_pk_bf16_f32 v98, v44, v45
	v_cvt_pk_bf16_f32 v99, v46, v47
	v_mov_b32_e32 v144, s5
	v_add3_u32 v161, s5, v119, v118
	v_add3_u32 v174, s5, v175, v118
	v_add_u32_e32 v163, 0x8000, v162
	s_waitcnt lgkmcnt(0)
	v_mfma_f32_32x32x16_bf16 v[80:95], v[100:103], v[104:107], v[80:95]
	ds_read_b128 v[100:103], v136 offset:64
	ds_read_b128 v[104:107], v136 offset:96
	v_add_u32_e32 v164, 0x8400, v162
	v_add_u32_e32 v165, 0x9000, v162
	v_add_u32_e32 v168, 0x9400, v162
	v_add_u32_e32 v169, 0xa000, v162
	v_add_u32_e32 v170, 0xa400, v162
	v_add_u32_e32 v171, 0xb000, v162
	s_waitcnt lgkmcnt(1)
	v_mfma_f32_32x32x16_bf16 v[64:79], v[100:103], v[108:111], v[64:79]
	ds_read_b128 v[100:103], v136 offset:8768
	ds_read_b128 v[124:127], v136 offset:8800
	v_add_u32_e32 v172, 0xb400, v162
	s_mulk_i32 s4, 0x4200
	s_add_i32 s3, s3, 1
	s_cmp_lg_u32 s3, 64
	s_waitcnt lgkmcnt(1)
	v_mfma_f32_32x32x16_bf16 v[80:95], v[100:103], v[108:111], v[80:95]
	v_cvt_pk_bf16_f32 v100, v24, v25
	v_cvt_pk_bf16_f32 v101, v26, v27
	v_cvt_pk_bf16_f32 v102, v28, v29
	v_cvt_pk_bf16_f32 v103, v30, v31
	v_cvt_pk_bf16_f32 v108, v8, v9
	v_cvt_pk_bf16_f32 v109, v10, v11
	v_cvt_pk_bf16_f32 v110, v12, v13
	v_mfma_f32_32x32x16_bf16 v[64:79], v[104:107], v[96:99], v[64:79]
	v_cvt_pk_bf16_f32 v104, v0, v1
	v_cvt_pk_bf16_f32 v105, v2, v3
	v_cvt_pk_bf16_f32 v106, v4, v5
	v_cvt_pk_bf16_f32 v107, v6, v7
	v_cvt_pk_bf16_f32 v111, v14, v15
	s_waitcnt lgkmcnt(0)
	v_mfma_f32_32x32x16_bf16 v[80:95], v[124:127], v[96:99], v[80:95]
	ds_read_b128 v[96:99], v136 offset:128
	ds_read_b128 v[124:127], v136 offset:160
	s_waitcnt lgkmcnt(1)
	v_mfma_f32_32x32x16_bf16 v[64:79], v[96:99], v[120:123], v[64:79]
	ds_read_b128 v[96:99], v136 offset:8832
	ds_read_b128 v[128:131], v136 offset:8864
	s_waitcnt lgkmcnt(2)
	v_mfma_f32_32x32x16_bf16 v[64:79], v[124:127], v[100:103], v[64:79]
	s_waitcnt lgkmcnt(1)
	v_mfma_f32_32x32x16_bf16 v[80:95], v[96:99], v[120:123], v[80:95]
	ds_read_b128 v[96:99], v136 offset:8896
	ds_read_b128 v[120:123], v136 offset:192
	ds_read_b128 v[132:135], v136 offset:224
	ds_read_b128 v[124:127], v136 offset:8928
	ds_read_b128 v[136:139], v161 offset:27680
	ds_read_b128 v[140:143], v161 offset:30208
	ds_read_b32 v160, v144 offset:49664
	ds_read_b128 v[144:147], v174 offset:17408
	ds_read_b128 v[148:151], v174 offset:17568
	s_waitcnt lgkmcnt(2)
; #define LAS __attribute__((address_space(3)))
; #define DR_BAR() do { asm volatile("s_waitcnt lgkmcnt(0)" ::: "memory"); __builtin_amdgcn_s_barrier(); asm volatile("" ::: "memory"); } while (0)
; __device__ __forceinline__ void delta_rec_task(const Params& P, LAS unsigned char* lds, int b, int h, int tid) {
;     ...
;             const LAS float* VB = (const LAS float*)(buf + DR_VB) + 32 * vb + n;
;             float Y[16];
; #pragma unroll
;             for (int r = 0; r < 16; ++r) Y[r] = VB[((r & 3) + 8 * (r >> 2) + 4 * hh) * 132] - X1[r];
;             const bf16x8 YB0 = pack8(Y[0], Y[1], Y[2], Y[3], Y[4], Y[5], Y[6], Y[7]), YB1 = pack8(Y[8], Y[9], Y[10], Y[11], Y[12], Y[13], Y[14], Y[15]);
;             f32x16 VN;
; #pragma unroll
;             for (int r = 0; r < 16; ++r) VN[r] = 0.f;
;             const LAS bf16* TI = (const LAS bf16*)(buf + DR_TI) + n * 40 + 8 * hh; const LAS bf16* AT = (const LAS bf16*)(buf + DR_AT) + n * 40 + 8 * hh;
;             VN = __builtin_amdgcn_mfma_f32_32x32x16_bf16(*(const LAS bf16x8*)TI, YB0, VN, 0, 0, 0);
;             VN = __builtin_amdgcn_mfma_f32_32x32x16_bf16(*(const LAS bf16x8*)(TI + 16), YB1, VN, 0, 0, 0);
;             const bf16x8 VB0 = pack8(VN[0], VN[1], VN[2], VN[3], VN[4], VN[5], VN[6], VN[7]), VB1 = pack8(VN[8], VN[9], VN[10], VN[11], VN[12], VN[13], VN[14], VN[15]);
;             P1 = __builtin_amdgcn_mfma_f32_32x32x16_bf16(*(const LAS bf16x8*)AT, VB0, P1, 0, 0, 0);
;             P1 = __builtin_amdgcn_mfma_f32_32x32x16_bf16(*(const LAS bf16x8*)(AT + 16), VB1, P1, 0, 0, 0);
;             const float egl = *(const LAS float*)(buf + DR_EGL);
;             const LAS bf16* KDT = (const LAS bf16*)(buf + DR_KDT) + n * 40 + 8 * hh;
; #pragma unroll
;             for (int kb = 0; kb < 4; ++kb) {
; #pragma unroll
;                 for (int r = 0; r < 16; ++r) S[kb][r] *= egl;
;                 S[kb] = __builtin_amdgcn_mfma_f32_32x32x16_bf16(*(const LAS bf16x8*)(KDT + kb * 32 * 40), VB0, S[kb], 0, 0, 0);
;                 S[kb] = __builtin_amdgcn_mfma_f32_32x32x16_bf16(*(const LAS bf16x8*)(KDT + kb * 32 * 40 + 16), VB1, S[kb], 0, 0, 0); }
;             LAS float* op = (LAS float*)(lds + DR_OB) + (c & 1) * 32 * 132 + 4 * hh * 132 + 32 * vb + n;
; #pragma unroll
;             for (int r = 0; r < 16; ++r) op[((r & 3) + 8 * (r >> 2)) * 132] = P1[r];
;             DR_BAR();
;         }
	v_pk_mul_f32 v[62:63], v[62:63], v[160:161] op_sel_hi:[1,0]
	v_pk_mul_f32 v[60:61], v[60:61], v[160:161] op_sel_hi:[1,0]
	v_mfma_f32_32x32x16_bf16 v[64:79], v[120:123], v[104:107], v[64:79]
	v_mul_f32_e64 v58, v58, v160
	v_mul_f32_e64 v59, v59, v160
	v_mul_f32_e64 v56, v56, v160
	v_mul_f32_e64 v57, v57, v160
	v_mul_f32_e64 v54, v54, v160
	v_mul_f32_e64 v55, v55, v160
	v_pk_mul_f32 v[52:53], v[52:53], v[160:161] op_sel_hi:[1,0]
	v_pk_mul_f32 v[50:51], v[50:51], v[160:161] op_sel_hi:[1,0]
	v_pk_mul_f32 v[48:49], v[48:49], v[160:161] op_sel_hi:[1,0]
	v_pk_mul_f32 v[46:47], v[46:47], v[160:161] op_sel_hi:[1,0]
	v_mfma_f32_32x32x16_bf16 v[80:95], v[128:131], v[100:103], v[80:95]
	ds_read_b128 v[128:131], v174 offset:17728
	ds_read_b128 v[152:155], v174 offset:17888
	ds_read_b128 v[100:103], v161 offset:27648
	ds_read_b128 v[156:159], v174 offset:17920
	ds_read2_b32 v[120:121], v163 offset1:132
	ds_read2_b32 v[122:123], v164 offset0:8 offset1:140
	v_pk_mul_f32 v[44:45], v[44:45], v[160:161] op_sel_hi:[1,0]
	v_pk_mul_f32 v[42:43], v[42:43], v[160:161] op_sel_hi:[1,0]
	v_pk_mul_f32 v[40:41], v[40:41], v[160:161] op_sel_hi:[1,0]
	v_pk_mul_f32 v[38:39], v[38:39], v[160:161] op_sel_hi:[1,0]
	v_pk_mul_f32 v[36:37], v[36:37], v[160:161] op_sel_hi:[1,0]
	v_mfma_f32_32x32x16_bf16 v[64:79], v[132:135], v[108:111], v[64:79]
	v_mul_f32_e64 v34, v34, v160
	v_mul_f32_e64 v35, v35, v160
	v_mul_f32_e64 v32, v32, v160
	v_mul_f32_e64 v33, v33, v160
	v_mul_f32_e64 v30, v30, v160
	v_mul_f32_e64 v31, v31, v160
	v_pk_mul_f32 v[28:29], v[28:29], v[160:161] op_sel_hi:[1,0]
	v_pk_mul_f32 v[26:27], v[26:27], v[160:161] op_sel_hi:[1,0]
	v_pk_mul_f32 v[24:25], v[24:25], v[160:161] op_sel_hi:[1,0]
	v_pk_mul_f32 v[22:23], v[22:23], v[160:161] op_sel_hi:[1,0]
	v_mfma_f32_32x32x16_bf16 v[80:95], v[96:99], v[104:107], v[80:95]
	ds_read2_b32 v[96:97], v165 offset0:32 offset1:164
	ds_read2_b32 v[98:99], v168 offset0:40 offset1:172
	ds_read2_b32 v[104:105], v169 offset0:64 offset1:196
	ds_read2_b32 v[162:163], v170 offset0:72 offset1:204
	ds_read2_b32 v[164:165], v171 offset0:96 offset1:228
	ds_read2_b32 v[168:169], v172 offset0:104 offset1:236
	s_waitcnt lgkmcnt(7)
	v_pk_add_f32 v[64:65], v[120:121], v[64:65] neg_lo:[0,1] neg_hi:[0,1]
	s_waitcnt lgkmcnt(6)
	v_pk_add_f32 v[66:67], v[122:123], v[66:67] neg_lo:[0,1] neg_hi:[0,1]
	s_waitcnt lgkmcnt(5)
	v_pk_add_f32 v[68:69], v[96:97], v[68:69] neg_lo:[0,1] neg_hi:[0,1]
	s_waitcnt lgkmcnt(4)
	v_pk_add_f32 v[70:71], v[98:99], v[70:71] neg_lo:[0,1] neg_hi:[0,1]
	v_cvt_pk_bf16_f32 v64, v64, v65
	v_cvt_pk_bf16_f32 v65, v66, v67
	v_cvt_pk_bf16_f32 v66, v68, v69
	v_cvt_pk_bf16_f32 v67, v70, v71
	v_mfma_f32_32x32x16_bf16 v[80:95], v[124:127], v[108:111], v[80:95]
	s_waitcnt lgkmcnt(3)
	v_add_f32_e64 v72, v104, -v72
	v_add_f32_e64 v73, v105, -v73
	s_waitcnt lgkmcnt(1)
	v_add_f32_e64 v68, v164, -v76
	v_add_f32_e64 v69, v165, -v77
	s_waitcnt lgkmcnt(0)
	v_pk_add_f32 v[70:71], v[168:169], v[78:79] neg_lo:[0,1] neg_hi:[0,1]
	v_pk_mul_f32 v[20:21], v[20:21], v[160:161] op_sel_hi:[1,0]
	v_pk_mul_f32 v[18:19], v[18:19], v[160:161] op_sel_hi:[1,0]
	v_pk_mul_f32 v[16:17], v[16:17], v[160:161] op_sel_hi:[1,0]
	v_pk_mul_f32 v[14:15], v[14:15], v[160:161] op_sel_hi:[1,0]
	v_mfma_f32_32x32x16_bf16 v[96:111], v[100:103], v[64:67], 0
	v_add_f32_e64 v66, v162, -v74
	v_add_f32_e64 v67, v163, -v75
	v_cvt_pk_bf16_f32 v64, v72, v73
	v_cvt_pk_bf16_f32 v65, v66, v67
	v_cvt_pk_bf16_f32 v66, v68, v69
	v_cvt_pk_bf16_f32 v67, v70, v71
	v_pk_mul_f32 v[12:13], v[12:13], v[160:161] op_sel_hi:[1,0]
	v_pk_mul_f32 v[10:11], v[10:11], v[160:161] op_sel_hi:[1,0]
	v_mfma_f32_32x32x16_bf16 v[96:111], v[136:139], v[64:67], v[96:111]
	v_mul_f32_e64 v8, v8, v160
	v_mul_f32_e64 v9, v9, v160
	v_mul_f32_e64 v6, v6, v160
	v_mul_f32_e64 v7, v7, v160
	v_mul_f32_e64 v4, v4, v160
	v_mul_f32_e64 v5, v5, v160
	v_pk_mul_f32 v[2:3], v[2:3], v[160:161] op_sel_hi:[1,0]
	v_pk_mul_f32 v[0:1], v[0:1], v[160:161] op_sel_hi:[1,0]
	v_add_u32_e32 v72, s4, v116
	v_add_u32_e32 v73, 0x400, v72
	s_nop 1
	v_cvt_pk_bf16_f32 v64, v96, v97
	v_cvt_pk_bf16_f32 v65, v98, v99
	v_cvt_pk_bf16_f32 v66, v100, v101
	v_cvt_pk_bf16_f32 v67, v102, v103
	v_cvt_pk_bf16_f32 v68, v104, v105
	v_cvt_pk_bf16_f32 v69, v106, v107
	v_mfma_f32_32x32x16_bf16 v[48:63], v[144:147], v[64:67], v[48:63]
	v_cvt_pk_bf16_f32 v70, v108, v109
	v_cvt_pk_bf16_f32 v71, v110, v111
	v_add_u32_e32 v74, 0x1000, v72
	v_add_u32_e32 v75, 0x1400, v72
	v_add_u32_e32 v76, 0x2000, v72
	v_add_u32_e32 v77, 0x2400, v72
	v_add_u32_e32 v78, 0x3000, v72
	v_mfma_f32_32x32x16_bf16 v[32:47], v[148:151], v[64:67], v[32:47]
	v_add_u32_e32 v79, 0x3400, v72
	v_mfma_f32_32x32x16_bf16 v[16:31], v[128:131], v[64:67], v[16:31]
	v_mfma_f32_32x32x16_bf16 v[0:15], v[152:155], v[64:67], v[0:15]
	v_mfma_f32_32x32x16_bf16 v[80:95], v[140:143], v[64:67], v[80:95]
	ds_read_b128 v[64:67], v174 offset:17440
	s_waitcnt lgkmcnt(0)
	v_mfma_f32_32x32x16_bf16 v[48:63], v[64:67], v[68:71], v[48:63]
	ds_read_b128 v[64:67], v174 offset:17600
	s_waitcnt lgkmcnt(0)
	v_mfma_f32_32x32x16_bf16 v[32:47], v[64:67], v[68:71], v[32:47]
	ds_read_b128 v[64:67], v174 offset:17760
	s_waitcnt lgkmcnt(0)
	v_mfma_f32_32x32x16_bf16 v[16:31], v[64:67], v[68:71], v[16:31]
	ds_read_b128 v[64:67], v161 offset:30240
	s_waitcnt lgkmcnt(0)
	v_mfma_f32_32x32x16_bf16 v[80:95], v[64:67], v[68:71], v[80:95]
	s_nop 11
	ds_write2_b32 v72, v80, v81 offset1:132
	ds_write2_b32 v73, v82, v83 offset0:8 offset1:140
	ds_write2_b32 v74, v84, v85 offset0:32 offset1:164
	ds_write2_b32 v75, v86, v87 offset0:40 offset1:172
	ds_write2_b32 v76, v88, v89 offset0:64 offset1:196
	ds_write2_b32 v77, v90, v91 offset0:72 offset1:204
	ds_write2_b32 v78, v92, v93 offset0:96 offset1:228
	ds_write2_b32 v79, v94, v95 offset0:104 offset1:236
	v_mfma_f32_32x32x16_bf16 v[0:15], v[156:159], v[68:71], v[0:15]
	s_waitcnt lgkmcnt(0)
	s_barrier
	s_cbranch_scc1 .LBB0_1833
	s_andn2_saveexec_b64 s[6:7], s[6:7]
	s_cbranch_execz .LBB0_1818

; #define LAS __attribute__((address_space(3)))
; __device__ __forceinline__ unsigned f2bf(float f) { return pk2(f, f) & 0xffffu; }
; __device__ __forceinline__ void unpack8(const u32x4 u, float* x) { x[0] = bflo(u.x); x[1] = bfhi(u.x); x[2] = bflo(u.y); x[3] = bfhi(u.y); x[4] = bflo(u.z); x[5] = bfhi(u.z); x[6] = bflo(u.w); x[7] = bfhi(u.w); }
; __device__ __forceinline__ int perm16(int e) { return (e & ~12) | ((e >> 1) & 4) | ((e << 1) & 8); }
; __device__ __forceinline__ void delta_rec_stage(LAS unsigned char* buf, int pt, const DeltaPre& dp) {
;     const int tt = pt >> 3, dg = pt & 7, d0 = dg * 16;
;     { LAS bf16* dst = (LAS bf16*)(buf + (pt < 128 ? DR_TI : DR_AT)) + ((pt & 127) >> 2) * 40 + (pt & 3) * 8; *(LAS u32x4*)dst = dp.tia; }
;     if (pt == 0) *(LAS float*)(buf + DR_EGL) = __expf(dp.gl);
;     const float eg = __expf(dp.gct), ekd = __expf(dp.gl - dp.gct);
;     const float fq = dp.nq * eg, fkb = dp.nk * dp.bet * eg, fkd = dp.nk * ekd, bet = dp.bet;
;     float k[16], q[16], v[16];
;     unpack8(dp.k0, k); unpack8(dp.k1, k + 8); unpack8(dp.q0, q); unpack8(dp.q1, q + 8); unpack8(dp.v0, v); unpack8(dp.v1, v + 8);
;     LAS bf16* KB = (LAS bf16*)(buf + DR_KB) + tt * 136 + d0; LAS bf16* QD = (LAS bf16*)(buf + DR_QD) + tt * 136 + d0;
;     *(LAS bf16x8*)KB = pack8(k[0] * fkb, k[1] * fkb, k[2] * fkb, k[3] * fkb, k[8] * fkb, k[9] * fkb, k[10] * fkb, k[11] * fkb);
;     *(LAS bf16x8*)(KB + 8) = pack8(k[4] * fkb, k[5] * fkb, k[6] * fkb, k[7] * fkb, k[12] * fkb, k[13] * fkb, k[14] * fkb, k[15] * fkb);
;     *(LAS bf16x8*)QD = pack8(q[0] * fq, q[1] * fq, q[2] * fq, q[3] * fq, q[8] * fq, q[9] * fq, q[10] * fq, q[11] * fq);
;     *(LAS bf16x8*)(QD + 8) = pack8(q[4] * fq, q[5] * fq, q[6] * fq, q[7] * fq, q[12] * fq, q[13] * fq, q[14] * fq, q[15] * fq);
;     LAS bf16* KDT = (LAS bf16*)(buf + DR_KDT) + d0 * 40 + perm16(tt);
; #pragma unroll
;     for (int e = 0; e < 16; ++e) KDT[e * 40] = (bf16)f2bf(k[e] * fkd);
;     LAS float* VB = (LAS float*)(buf + DR_VB) + tt * 132 + d0;
; #pragma unroll
;     for (int e4 = 0; e4 < 4; ++e4) *(LAS f32x4*)(VB + 4 * e4) = (f32x4){v[4 * e4] * bet, v[4 * e4 + 1] * bet, v[4 * e4 + 2] * bet, v[4 * e4 + 3] * bet};
; }
.LBB0_1837:
	s_or_b64 exec, exec, s[18:19]
	v_lshrrev_b32_e32 v33, 1, v22
	v_and_b32_e32 v128, 4, v33
	v_lshlrev_b32_e32 v33, 1, v22
	v_and_b32_e32 v129, 8, v33
	v_mul_f32_e32 v33, 0x3fb8aa3b, v117
	v_sub_f32_e32 v34, v118, v117
	v_exp_f32_e32 v33, v33
	v_mul_f32_e32 v34, 0x3fb8aa3b, v34
	v_exp_f32_e32 v34, v34
	s_movk_i32 s18, 0x88
	v_mul_f32_e32 v35, v119, v110
	v_mul_lo_u32 v32, v22, s18
	v_mul_f32_e32 v42, v35, v33
	v_lshlrev_b32_e32 v52, 16, v84
	v_and_b32_e32 v53, 0xffff0000, v84
	v_lshlrev_b32_e32 v54, 16, v85
	v_and_b32_e32 v55, 0xffff0000, v85
	v_lshlrev_b32_e32 v56, 16, v80
	v_and_b32_e32 v57, 0xffff0000, v80
	v_lshlrev_b32_e32 v60, 16, v81
	v_and_b32_e32 v61, 0xffff0000, v81
	v_mul_f32_e32 v40, v120, v33
	v_mul_f32_e32 v117, v119, v34
	v_lshlrev_b32_e32 v91, 1, v32
	v_pk_mul_f32 v[32:33], v[42:43], v[52:53] op_sel_hi:[0,1]
	v_pk_mul_f32 v[34:35], v[42:43], v[54:55] op_sel_hi:[0,1]
	v_pk_mul_f32 v[58:59], v[42:43], v[56:57] op_sel_hi:[0,1]
	v_pk_mul_f32 v[62:63], v[42:43], v[60:61] op_sel_hi:[0,1]
	v_add3_u32 v118, 0, v91, v114
	v_cvt_pk_bf16_f32 v32, v32, v33
	v_cvt_pk_bf16_f32 v33, v34, v35
	v_cvt_pk_bf16_f32 v34, v58, v59
	v_cvt_pk_bf16_f32 v35, v62, v63
	v_lshlrev_b32_e32 v58, 16, v86
	v_and_b32_e32 v59, 0xffff0000, v86
	v_lshlrev_b32_e32 v62, 16, v87
	v_and_b32_e32 v63, 0xffff0000, v87
	v_lshlrev_b32_e32 v84, 16, v82
	v_and_b32_e32 v85, 0xffff0000, v82
	v_lshlrev_b32_e32 v86, 16, v83
	v_and_b32_e32 v87, 0xffff0000, v83
	ds_write_b128 v118, v[32:35] offset:49680
	v_pk_mul_f32 v[32:33], v[42:43], v[58:59] op_sel_hi:[0,1]
	v_pk_mul_f32 v[34:35], v[42:43], v[62:63] op_sel_hi:[0,1]
	v_pk_mul_f32 v[80:81], v[42:43], v[84:85] op_sel_hi:[0,1]
	v_pk_mul_f32 v[42:43], v[42:43], v[86:87] op_sel_hi:[0,1]
	v_cvt_pk_bf16_f32 v32, v32, v33
	v_cvt_pk_bf16_f32 v33, v34, v35
	v_cvt_pk_bf16_f32 v34, v80, v81
	v_cvt_pk_bf16_f32 v35, v42, v43
	ds_write_b128 v118, v[32:35] offset:49696
	v_lshlrev_b32_e32 v32, 16, v76
	v_and_b32_e32 v33, 0xffff0000, v76
	v_lshlrev_b32_e32 v34, 16, v77
	v_and_b32_e32 v35, 0xffff0000, v77
	v_lshlrev_b32_e32 v42, 16, v72
	v_and_b32_e32 v43, 0xffff0000, v72
	v_lshlrev_b32_e32 v72, 16, v73
	v_and_b32_e32 v73, 0xffff0000, v73
	v_pk_mul_f32 v[32:33], v[40:41], v[32:33] op_sel_hi:[0,1]
	v_pk_mul_f32 v[34:35], v[40:41], v[34:35] op_sel_hi:[0,1]
	v_pk_mul_f32 v[42:43], v[40:41], v[42:43] op_sel_hi:[0,1]
	v_pk_mul_f32 v[72:73], v[40:41], v[72:73] op_sel_hi:[0,1]
	v_cvt_pk_bf16_f32 v32, v32, v33
	v_cvt_pk_bf16_f32 v33, v34, v35
	v_cvt_pk_bf16_f32 v34, v42, v43
	v_cvt_pk_bf16_f32 v35, v72, v73
	s_movk_i32 s18, 0x210
	ds_write_b128 v118, v[32:35] offset:58384
	v_lshlrev_b32_e32 v32, 16, v78
	v_and_b32_e32 v33, 0xffff0000, v78
	v_lshlrev_b32_e32 v34, 16, v79
	v_and_b32_e32 v35, 0xffff0000, v79
	v_lshlrev_b32_e32 v42, 16, v74
	v_and_b32_e32 v43, 0xffff0000, v74
	v_lshlrev_b32_e32 v72, 16, v75
	v_and_b32_e32 v73, 0xffff0000, v75
	v_mul_lo_u32 v88, v22, s18
	s_add_i32 s18, 0, 0x18420
	v_pk_mul_f32 v[32:33], v[40:41], v[32:33] op_sel_hi:[0,1]
	v_pk_mul_f32 v[34:35], v[40:41], v[34:35] op_sel_hi:[0,1]
	v_pk_mul_f32 v[42:43], v[40:41], v[42:43] op_sel_hi:[0,1]
	v_pk_mul_f32 v[40:41], v[40:41], v[72:73] op_sel_hi:[0,1]
	v_mul_u32_u24_e32 v90, 5, v27
	v_and_b32_e32 v127, -13, v22
	v_add3_u32 v89, s18, v88, v111
	v_cvt_pk_bf16_f32 v32, v32, v33
	v_cvt_pk_bf16_f32 v33, v34, v35
	v_cvt_pk_bf16_f32 v34, v42, v43
	v_cvt_pk_bf16_f32 v35, v40, v41
	s_add_i32 s18, 0, 0x10610
	v_lshlrev_b32_e32 v80, 1, v128
	ds_write_b128 v118, v[32:35] offset:58400
	v_add3_u32 v32, s18, v90, v80
	v_lshlrev_b32_e32 v81, 1, v127
	v_lshlrev_b32_e32 v82, 1, v129
	v_mul_f32_e32 v33, v117, v52
	v_add3_u32 v32, v32, v81, v82
	v_cvt_pk_bf16_f32 v33, v33, s0
	ds_write_b16 v32, v33
	v_mul_f32_e32 v33, v117, v53
	v_cvt_pk_bf16_f32 v33, v33, s0
	ds_write_b16 v32, v33 offset:640
	v_mul_f32_e32 v33, v117, v54
	v_cvt_pk_bf16_f32 v33, v33, s0
	ds_write_b16 v32, v33 offset:1280
	v_mul_f32_e32 v33, v117, v55
	v_cvt_pk_bf16_f32 v33, v33, s0
	ds_write_b16 v32, v33 offset:1920
	v_mul_f32_e32 v33, v117, v58
	v_cvt_pk_bf16_f32 v33, v33, s0
	ds_write_b16 v32, v33 offset:2560
	v_mul_f32_e32 v33, v117, v59
	v_cvt_pk_bf16_f32 v33, v33, s0
	ds_write_b16 v32, v33 offset:3200
	v_mul_f32_e32 v33, v117, v62
	v_cvt_pk_bf16_f32 v33, v33, s0
	ds_write_b16 v32, v33 offset:3840
	v_mul_f32_e32 v33, v117, v63
	v_cvt_pk_bf16_f32 v33, v33, s0
	ds_write_b16 v32, v33 offset:4480
	v_mul_f32_e32 v33, v117, v56
	v_cvt_pk_bf16_f32 v33, v33, s0
	ds_write_b16 v32, v33 offset:5120
	v_mul_f32_e32 v33, v117, v57
	v_cvt_pk_bf16_f32 v33, v33, s0
	ds_write_b16 v32, v33 offset:5760
	v_mul_f32_e32 v33, v117, v60
	v_cvt_pk_bf16_f32 v33, v33, s0
	ds_write_b16 v32, v33 offset:6400
	v_mul_f32_e32 v33, v117, v61
	v_cvt_pk_bf16_f32 v33, v33, s0
	ds_write_b16 v32, v33 offset:7040
	v_mul_f32_e32 v33, v117, v84
	v_cvt_pk_bf16_f32 v33, v33, s0
	ds_write_b16 v32, v33 offset:7680
	v_mul_f32_e32 v33, v117, v85
	v_cvt_pk_bf16_f32 v33, v33, s0
	ds_write_b16 v32, v33 offset:8320
	v_mul_f32_e32 v33, v117, v86
	v_cvt_pk_bf16_f32 v33, v33, s0
	ds_write_b16 v32, v33 offset:8960
	v_mul_f32_e32 v33, v117, v87
	v_cvt_pk_bf16_f32 v33, v33, s0
	ds_write_b16 v32, v33 offset:9600
	s_add_i32 s18, 0, 0x14210
	v_lshlrev_b32_e32 v32, 16, v68
	v_and_b32_e32 v33, 0xffff0000, v68
	v_lshlrev_b32_e32 v34, 16, v69
	v_and_b32_e32 v35, 0xffff0000, v69
	v_add3_u32 v40, s18, v88, v111
	v_pk_mul_f32 v[32:33], v[110:111], v[32:33] op_sel_hi:[0,1]
	v_pk_mul_f32 v[34:35], v[110:111], v[34:35] op_sel_hi:[0,1]
	ds_write_b128 v40, v[32:35]
	v_lshlrev_b32_e32 v32, 16, v70
	v_and_b32_e32 v33, 0xffff0000, v70
	v_lshlrev_b32_e32 v34, 16, v71
	v_and_b32_e32 v35, 0xffff0000, v71
	v_pk_mul_f32 v[32:33], v[110:111], v[32:33] op_sel_hi:[0,1]
	v_pk_mul_f32 v[34:35], v[110:111], v[34:35] op_sel_hi:[0,1]
	ds_write_b128 v40, v[32:35] offset:16
	v_lshlrev_b32_e32 v32, 16, v64
	v_and_b32_e32 v33, 0xffff0000, v64
	v_lshlrev_b32_e32 v34, 16, v65
	v_and_b32_e32 v35, 0xffff0000, v65
	v_pk_mul_f32 v[32:33], v[110:111], v[32:33] op_sel_hi:[0,1]
	v_pk_mul_f32 v[34:35], v[110:111], v[34:35] op_sel_hi:[0,1]
	ds_write_b128 v40, v[32:35] offset:32
	v_lshlrev_b32_e32 v32, 16, v66
	v_and_b32_e32 v33, 0xffff0000, v66
	v_lshlrev_b32_e32 v34, 16, v67
	v_and_b32_e32 v35, 0xffff0000, v67
	v_pk_mul_f32 v[32:33], v[110:111], v[32:33] op_sel_hi:[0,1]
	v_pk_mul_f32 v[34:35], v[110:111], v[34:35] op_sel_hi:[0,1]
	ds_write_b128 v40, v[32:35] offset:48
	v_lshl_add_u64 v[32:33], v[20:21], 0, s[12:13]
	v_and_b32_e32 v20, 0x7f, v26
	v_lshlrev_b32_e32 v20, 4, v20
	v_lshl_add_u64 v[32:33], v[32:33], 0, v[20:21]
	v_lshl_add_u64 v[24:25], s[4:5], 0, v[24:25]
	v_add_lshl_u32 v20, s20, v27, 1
	v_lshl_add_u64 v[72:73], v[24:25], 0, v[20:21]
	v_and_b32_e32 v20, 7, v26
	s_waitcnt lgkmcnt(0)
	s_barrier
; __device__ __forceinline__ unsigned char* karg_ws() { return *(volatile KAS ucptr_t*)((const KAS char*)__builtin_amdgcn_kernarg_segment_ptr() + 264); }
; __device__ __forceinline__ void delta_rec_task(const Params& P, LAS unsigned char* lds, int b, int h, int tid) {
;     ...
;         bf16* zgp = (bf16*)(karg_ws() + WS_Z + 5 * ZB) + ((size_t)b * SEQ + (pt >> 3)) * D + h * 128 + (pt & 7) * 16;
;         u32x4 zc0 = {0u, 0u, 0u, 0u}, zc1 = zc0, zn0, zn1;
;     ...
;         for (int c = 0; c < NC; ++c) {
;             if (c > 0) { dcur = dnxt; zc0 = zn0; zc1 = zn1; }
;             if (c + 2 < NC) delta_pre_load(b, h, c + 2, pt, dnxt);
;             zn0 = *(const u32x4*)(zgp + (size_t)c * 32 * D); zn1 = *(const u32x4*)(zgp + (size_t)c * 32 * D + 8);
	v_lshlrev_b64 v[74:75], 2, v[22:23]
	v_lshl_add_u64 v[22:23], v[24:25], 0, s[14:15]
	v_lshlrev_b32_e32 v20, 5, v20
	s_mov_b64 s[12:13], 0x1800
	v_lshl_add_u64 v[20:21], v[22:23], 0, v[20:21]
	v_lshl_add_u64 v[70:71], v[32:33], 0, s[12:13]
	s_lshl_b64 s[4:5], s[2:3], 13
	v_lshl_add_u64 v[76:77], s[16:17], 0, v[20:21]
	s_mov_b64 s[12:13], 0
	s_mov_b64 s[16:17], 0xb130000
	s_mov_b64 s[18:19], 0x3030000
	s_mov_b64 s[20:21], 0xd170000
	s_mov_b32 s3, 0xb130000
	s_mov_b32 s14, 0x3030000
	s_mov_b32 s34, 0xd170000
	s_mov_b32 s35, 0x2880000
	v_mov_b32_e32 v69, 0x2880000
	s_mov_b64 s[22:23], 0xf190000
	v_mov_b32_e32 v83, 0x358637bd
	s_mov_b64 s[24:25], 0x800
	s_mov_b32 s36, s15

; #define LAS __attribute__((address_space(3)))
; __device__ __forceinline__ unsigned f2bf(float f) { return pk2(f, f) & 0xffffu; }
; __device__ __forceinline__ int perm16(int e) { return (e & ~12) | ((e >> 1) & 4) | ((e << 1) & 8); }
; __device__ __forceinline__ void delta_rec_stage(LAS unsigned char* buf, int pt, const DeltaPre& dp) {
;     const int tt = pt >> 3, dg = pt & 7, d0 = dg * 16;
;     { LAS bf16* dst = (LAS bf16*)(buf + (pt < 128 ? DR_TI : DR_AT)) + ((pt & 127) >> 2) * 40 + (pt & 3) * 8; *(LAS u32x4*)dst = dp.tia; }
;     if (pt == 0) *(LAS float*)(buf + DR_EGL) = __expf(dp.gl);
;     const float eg = __expf(dp.gct), ekd = __expf(dp.gl - dp.gct);
;     const float fq = dp.nq * eg, fkb = dp.nk * dp.bet * eg, fkd = dp.nk * ekd, bet = dp.bet;
;     float k[16], q[16], v[16];
;     unpack8(dp.k0, k); unpack8(dp.k1, k + 8); unpack8(dp.q0, q); unpack8(dp.q1, q + 8); unpack8(dp.v0, v); unpack8(dp.v1, v + 8);
;     LAS bf16* KB = (LAS bf16*)(buf + DR_KB) + tt * 136 + d0; LAS bf16* QD = (LAS bf16*)(buf + DR_QD) + tt * 136 + d0;
;     *(LAS bf16x8*)KB = pack8(k[0] * fkb, k[1] * fkb, k[2] * fkb, k[3] * fkb, k[8] * fkb, k[9] * fkb, k[10] * fkb, k[11] * fkb);
;     *(LAS bf16x8*)(KB + 8) = pack8(k[4] * fkb, k[5] * fkb, k[6] * fkb, k[7] * fkb, k[12] * fkb, k[13] * fkb, k[14] * fkb, k[15] * fkb);
;     *(LAS bf16x8*)QD = pack8(q[0] * fq, q[1] * fq, q[2] * fq, q[3] * fq, q[8] * fq, q[9] * fq, q[10] * fq, q[11] * fq);
;     *(LAS bf16x8*)(QD + 8) = pack8(q[4] * fq, q[5] * fq, q[6] * fq, q[7] * fq, q[12] * fq, q[13] * fq, q[14] * fq, q[15] * fq);
;     LAS bf16* KDT = (LAS bf16*)(buf + DR_KDT) + d0 * 40 + perm16(tt);
; #pragma unroll
;     for (int e = 0; e < 16; ++e) KDT[e * 40] = (bf16)f2bf(k[e] * fkd);
;     LAS float* VB = (LAS float*)(buf + DR_VB) + tt * 132 + d0;
; #pragma unroll
;     for (int e4 = 0; e4 < 4; ++e4) *(LAS f32x4*)(VB + 4 * e4) = (f32x4){v[4 * e4] * bet, v[4 * e4 + 1] * bet, v[4 * e4 + 2] * bet, v[4 * e4 + 3] * bet};
; }
; __device__ __forceinline__ void delta_out_norm(const LAS float* ob, int pt, const float* dn16, const u32x4 z0, const u32x4 z1, bf16* dst) {
;     const LAS float* p = ob + (pt >> 3) * 132 + (pt & 7) * 16;
;     float o[16], z[16];
; #pragma unroll
;     for (int e4 = 0; e4 < 4; ++e4) { const f32x4 t = *(const LAS f32x4*)(p + 4 * e4); o[4 * e4] = t[0]; o[4 * e4 + 1] = t[1]; o[4 * e4 + 2] = t[2]; o[4 * e4 + 3] = t[3]; }
.LBB0_1840:
	s_or_b64 exec, exec, s[26:27]
	v_mul_f32_e32 v110, 0x3fb8aa3b, v123
	v_exp_f32_e32 v117, v110
	v_sub_f32_e32 v110, v124, v123
	v_mul_f32_e32 v110, 0x3fb8aa3b, v110
	v_exp_f32_e32 v119, v110
	v_mul_f32_e32 v118, v116, v125
	v_mul_f32_e32 v118, v117, v118
	v_lshlrev_b32_e32 v128, 16, v48
	v_and_b32_e32 v129, 0xffff0000, v48
	v_lshlrev_b32_e32 v48, 16, v49
	v_and_b32_e32 v49, 0xffff0000, v49
	v_lshlrev_b32_e32 v130, 16, v44
	v_and_b32_e32 v131, 0xffff0000, v44
	v_lshlrev_b32_e32 v134, 16, v45
	v_and_b32_e32 v135, 0xffff0000, v45
	v_mul_f32_e32 v110, v117, v126
	v_mul_f32_e32 v117, v125, v119
	v_pk_mul_f32 v[124:125], v[118:119], v[128:129] op_sel_hi:[0,1]
	v_pk_mul_f32 v[126:127], v[118:119], v[48:49] op_sel_hi:[0,1]
	v_pk_mul_f32 v[132:133], v[118:119], v[130:131] op_sel_hi:[0,1]
	v_pk_mul_f32 v[44:45], v[118:119], v[134:135] op_sel_hi:[0,1]
	v_add3_u32 v120, s37, v91, v114
	v_cvt_pk_bf16_f32 v124, v124, v125
	v_cvt_pk_bf16_f32 v125, v126, v127
	v_cvt_pk_bf16_f32 v126, v132, v133
	v_cvt_pk_bf16_f32 v127, v44, v45
	ds_write_b128 v120, v[124:127]
	v_lshlrev_b32_e32 v124, 16, v50
	v_and_b32_e32 v125, 0xffff0000, v50
	v_lshlrev_b32_e32 v50, 16, v51
	v_and_b32_e32 v51, 0xffff0000, v51
	v_lshlrev_b32_e32 v132, 16, v46
	v_and_b32_e32 v133, 0xffff0000, v46
	v_lshlrev_b32_e32 v138, 16, v47
	v_and_b32_e32 v139, 0xffff0000, v47
	v_pk_mul_f32 v[44:45], v[118:119], v[124:125] op_sel_hi:[0,1]
	v_pk_mul_f32 v[126:127], v[118:119], v[50:51] op_sel_hi:[0,1]
	v_pk_mul_f32 v[136:137], v[118:119], v[132:133] op_sel_hi:[0,1]
	v_pk_mul_f32 v[118:119], v[118:119], v[138:139] op_sel_hi:[0,1]
	v_cvt_pk_bf16_f32 v44, v44, v45
	v_cvt_pk_bf16_f32 v45, v126, v127
	v_cvt_pk_bf16_f32 v46, v136, v137
	v_cvt_pk_bf16_f32 v47, v118, v119
	ds_write_b128 v120, v[44:47] offset:16
	v_lshlrev_b32_e32 v44, 16, v36
	v_and_b32_e32 v45, 0xffff0000, v36
	v_lshlrev_b32_e32 v36, 16, v37
	v_and_b32_e32 v37, 0xffff0000, v37
	v_lshlrev_b32_e32 v46, 16, v28
	v_and_b32_e32 v47, 0xffff0000, v28
	v_lshlrev_b32_e32 v28, 16, v29
	v_and_b32_e32 v29, 0xffff0000, v29
	v_pk_mul_f32 v[44:45], v[110:111], v[44:45] op_sel_hi:[0,1]
	v_pk_mul_f32 v[36:37], v[110:111], v[36:37] op_sel_hi:[0,1]
	v_pk_mul_f32 v[46:47], v[110:111], v[46:47] op_sel_hi:[0,1]
	v_pk_mul_f32 v[28:29], v[110:111], v[28:29] op_sel_hi:[0,1]
	v_cvt_pk_bf16_f32 v44, v44, v45
	v_cvt_pk_bf16_f32 v45, v36, v37
	v_cvt_pk_bf16_f32 v46, v46, v47
	v_cvt_pk_bf16_f32 v47, v28, v29
	v_lshlrev_b32_e32 v28, 16, v38
	v_and_b32_e32 v29, 0xffff0000, v38
	v_lshlrev_b32_e32 v36, 16, v39
	v_and_b32_e32 v37, 0xffff0000, v39
	v_lshlrev_b32_e32 v38, 16, v30
	v_and_b32_e32 v39, 0xffff0000, v30
	v_lshlrev_b32_e32 v30, 16, v31
	v_and_b32_e32 v31, 0xffff0000, v31
	ds_write_b128 v120, v[44:47] offset:8704
	v_pk_mul_f32 v[28:29], v[110:111], v[28:29] op_sel_hi:[0,1]
	v_pk_mul_f32 v[36:37], v[110:111], v[36:37] op_sel_hi:[0,1]
	v_pk_mul_f32 v[38:39], v[110:111], v[38:39] op_sel_hi:[0,1]
	v_pk_mul_f32 v[44:45], v[110:111], v[30:31] op_sel_hi:[0,1]
	v_cvt_pk_bf16_f32 v28, v28, v29
	v_cvt_pk_bf16_f32 v29, v36, v37
	v_cvt_pk_bf16_f32 v30, v38, v39
	v_cvt_pk_bf16_f32 v31, v44, v45
	ds_write_b128 v120, v[28:31] offset:8720
	v_add3_u32 v28, s37, v90, v80
	v_mul_f32_e32 v29, v117, v128
	v_add3_u32 v28, v28, v81, v82
	v_cvt_pk_bf16_f32 v29, v29, s0
	ds_write_b16 v28, v29 offset:17408
	v_mul_f32_e32 v29, v117, v129
	v_cvt_pk_bf16_f32 v29, v29, s0
	ds_write_b16 v28, v29 offset:18048
	v_mul_f32_e32 v29, v117, v48
	v_cvt_pk_bf16_f32 v29, v29, s0
	ds_write_b16 v28, v29 offset:18688
	v_mul_f32_e32 v29, v117, v49
	v_cvt_pk_bf16_f32 v29, v29, s0
	ds_write_b16 v28, v29 offset:19328
	v_mul_f32_e32 v29, v117, v124
	v_cvt_pk_bf16_f32 v29, v29, s0
	ds_write_b16 v28, v29 offset:19968
	v_mul_f32_e32 v29, v117, v125
	v_cvt_pk_bf16_f32 v29, v29, s0
	ds_write_b16 v28, v29 offset:20608
	v_mul_f32_e32 v29, v117, v50
	v_cvt_pk_bf16_f32 v29, v29, s0
	ds_write_b16 v28, v29 offset:21248
	v_mul_f32_e32 v29, v117, v51
	v_cvt_pk_bf16_f32 v29, v29, s0
	ds_write_b16 v28, v29 offset:21888
	v_mul_f32_e32 v29, v117, v130
	v_cvt_pk_bf16_f32 v29, v29, s0
	ds_write_b16 v28, v29 offset:22528
	v_mul_f32_e32 v29, v117, v131
	v_cvt_pk_bf16_f32 v29, v29, s0
	ds_write_b16 v28, v29 offset:23168
	v_mul_f32_e32 v29, v117, v134
	v_cvt_pk_bf16_f32 v29, v29, s0
	ds_write_b16 v28, v29 offset:23808
	v_mul_f32_e32 v29, v117, v135
	v_cvt_pk_bf16_f32 v29, v29, s0
	ds_write_b16 v28, v29 offset:24448
	v_mul_f32_e32 v29, v117, v132
	v_cvt_pk_bf16_f32 v29, v29, s0
	ds_write_b16 v28, v29 offset:25088
	v_mul_f32_e32 v29, v117, v133
	v_cvt_pk_bf16_f32 v29, v29, s0
	ds_write_b16 v28, v29 offset:25728
	v_mul_f32_e32 v29, v117, v138
	v_cvt_pk_bf16_f32 v29, v29, s0
	ds_write_b16 v28, v29 offset:26368
	v_mul_f32_e32 v29, v117, v139
	v_cvt_pk_bf16_f32 v29, v29, s0
	ds_write_b16 v28, v29 offset:27008
	v_lshlrev_b32_e32 v28, 16, v16
	v_and_b32_e32 v29, 0xffff0000, v16
	v_lshlrev_b32_e32 v16, 16, v17
	v_and_b32_e32 v17, 0xffff0000, v17
	v_pk_mul_f32 v[30:31], v[116:117], v[16:17] op_sel_hi:[0,1]
	v_lshlrev_b32_e32 v16, 16, v18
	v_and_b32_e32 v17, 0xffff0000, v18
	v_lshlrev_b32_e32 v18, 16, v19
	v_and_b32_e32 v19, 0xffff0000, v19
	v_add3_u32 v110, s37, v88, v111
	v_pk_mul_f32 v[16:17], v[116:117], v[16:17] op_sel_hi:[0,1]
	v_pk_mul_f32 v[18:19], v[116:117], v[18:19] op_sel_hi:[0,1]
	s_and_b32 s26, s15, 32
	ds_write_b128 v110, v[16:19] offset:32784
	v_lshlrev_b32_e32 v16, 16, v12
	v_and_b32_e32 v17, 0xffff0000, v12
	v_lshlrev_b32_e32 v12, 16, v13
	v_and_b32_e32 v13, 0xffff0000, v13
	s_mulk_i32 s26, 0x210
	v_pk_mul_f32 v[16:17], v[116:117], v[16:17] op_sel_hi:[0,1]
	v_pk_mul_f32 v[18:19], v[116:117], v[12:13] op_sel_hi:[0,1]
	v_add_u32_e32 v44, s26, v89
	ds_write_b128 v110, v[16:19] offset:32800
	ds_read_b128 v[16:19], v44
	v_pk_mul_f32 v[28:29], v[116:117], v[28:29] op_sel_hi:[0,1]
	ds_write_b128 v110, v[28:31] offset:32768
	ds_read_b128 v[28:31], v44 offset:16
	ds_read_b128 v[36:39], v44 offset:32
	ds_read_b128 v[44:47], v44 offset:48
	v_lshlrev_b32_e32 v12, 16, v14
	s_waitcnt lgkmcnt(4)
; #define LAS __attribute__((address_space(3)))
; __device__ __forceinline__ float rsq_f(float x) { return __builtin_amdgcn_rsqf(x); }
; __device__ __forceinline__ float red8(float x) { x += dpp_f<0xB1>(x); x += dpp_f<0x4E>(x); x += dpp_f<0x141>(x); return x; }
; __device__ __forceinline__ void unpack8(const u32x4 u, float* x) { x[0] = bflo(u.x); x[1] = bfhi(u.x); x[2] = bflo(u.y); x[3] = bfhi(u.y); x[4] = bflo(u.z); x[5] = bfhi(u.z); x[6] = bflo(u.w); x[7] = bfhi(u.w); }
; __device__ __forceinline__ void delta_out_norm(const LAS float* ob, int pt, const float* dn16, const u32x4 z0, const u32x4 z1, bf16* dst) {
;     const LAS float* p = ob + (pt >> 3) * 132 + (pt & 7) * 16;
;     float o[16], z[16];
; #pragma unroll
;     for (int e4 = 0; e4 < 4; ++e4) { const f32x4 t = *(const LAS f32x4*)(p + 4 * e4); o[4 * e4] = t[0]; o[4 * e4 + 1] = t[1]; o[4 * e4 + 2] = t[2]; o[4 * e4 + 3] = t[3]; }
;     float ss = 0.f;
; #pragma unroll
;     for (int e = 0; e < 16; ++e) ss += o[e] * o[e];
;     ss = red8(ss);
;     const float rstd = rsq_f(ss * (1.f / 128.f) + EPS);
;     unpack8(z0, z); unpack8(z1, z + 8);
; #pragma unroll
;     for (int e = 0; e < 16; ++e) o[e] = o[e] * rstd * dn16[e] * z[e];
;     *(bf16x8*)dst = pack8(o[0], o[1], o[2], o[3], o[4], o[5], o[6], o[7]); *(bf16x8*)(dst + 8) = pack8(o[8], o[9], o[10], o[11], o[12], o[13], o[14], o[15]);
; }
	v_mul_f32_e32 v50, v17, v17
	v_fmac_f32_e32 v50, v16, v16
	v_fmac_f32_e32 v50, v18, v18
	v_fmac_f32_e32 v50, v19, v19
	s_waitcnt lgkmcnt(2)
	v_fmac_f32_e32 v50, v28, v28
	v_fmac_f32_e32 v50, v29, v29
	v_fmac_f32_e32 v50, v30, v30
	v_fmac_f32_e32 v50, v31, v31
	s_waitcnt lgkmcnt(1)
	v_fmac_f32_e32 v50, v36, v36
	v_fmac_f32_e32 v50, v37, v37
	v_pk_mul_f32 v[48:49], v[38:39], v[38:39]
	v_and_b32_e32 v13, 0xffff0000, v14
	v_lshlrev_b32_e32 v14, 16, v15
	v_and_b32_e32 v15, 0xffff0000, v15
	v_add_f32_e32 v48, v48, v50
	v_pk_mul_f32 v[12:13], v[116:117], v[12:13] op_sel_hi:[0,1]
	v_pk_mul_f32 v[14:15], v[116:117], v[14:15] op_sel_hi:[0,1]
	v_add_f32_e32 v116, v49, v48
	s_waitcnt lgkmcnt(0)
	v_pk_mul_f32 v[50:51], v[44:45], v[44:45]
	v_pk_mul_f32 v[48:49], v[46:47], v[46:47]
	v_add_f32_e32 v50, v50, v116
	v_add_f32_e32 v50, v51, v50
	v_add_f32_e32 v48, v48, v50
	v_add_f32_e32 v48, v49, v48
	ds_write_b128 v110, v[12:15] offset:32816
	s_waitcnt vmcnt(15)
	v_lshlrev_b32_e32 v12, 16, v8
	v_add_f32_dpp v48, v48, v48 quad_perm:[1,0,3,2] row_mask:0xf bank_mask:0xf bound_ctrl:1
	v_and_b32_e32 v13, 0xffff0000, v8
	v_lshlrev_b32_e32 v8, 16, v9
	v_add_f32_dpp v48, v48, v48 quad_perm:[2,3,0,1] row_mask:0xf bank_mask:0xf bound_ctrl:1
	v_and_b32_e32 v9, 0xffff0000, v9
	s_add_i32 s36, s36, 1
	v_add_f32_dpp v48, v48, v48 row_half_mirror row_mask:0xf bank_mask:0xf bound_ctrl:1
	v_fmamk_f32 v48, v48, 0x3c000000, v83
	v_rsq_f32_e32 v48, v48
	s_add_u32 s12, s12, 0x10000
	s_addc_u32 s13, s13, 0
	s_add_u32 s4, s4, 0x80
	v_pk_mul_f32 v[14:15], v[16:17], v[48:49] op_sel_hi:[1,0]
	v_pk_mul_f32 v[16:17], v[28:29], v[48:49] op_sel_hi:[1,0]
	v_pk_mul_f32 v[14:15], v[102:103], v[14:15]
	v_pk_mul_f32 v[16:17], v[98:99], v[16:17]
	v_pk_mul_f32 v[12:13], v[14:15], v[12:13]
	v_pk_mul_f32 v[14:15], v[18:19], v[48:49] op_sel_hi:[1,0]
	v_pk_mul_f32 v[18:19], v[36:37], v[48:49] op_sel_hi:[1,0]
	v_pk_mul_f32 v[14:15], v[100:101], v[14:15]
	v_pk_mul_f32 v[18:19], v[94:95], v[18:19]
	v_pk_mul_f32 v[8:9], v[14:15], v[8:9]
	v_lshlrev_b32_e32 v14, 16, v10
	v_and_b32_e32 v15, 0xffff0000, v10
	v_pk_mul_f32 v[14:15], v[16:17], v[14:15]
	v_pk_mul_f32 v[16:17], v[30:31], v[48:49] op_sel_hi:[1,0]
	v_lshlrev_b32_e32 v10, 16, v11
	v_and_b32_e32 v11, 0xffff0000, v11
	v_pk_mul_f32 v[16:17], v[96:97], v[16:17]
	v_pk_mul_f32 v[28:29], v[44:45], v[48:49] op_sel_hi:[1,0]
	v_pk_mul_f32 v[10:11], v[16:17], v[10:11]
	s_waitcnt vmcnt(14)
	v_lshlrev_b32_e32 v16, 16, v4
	v_and_b32_e32 v17, 0xffff0000, v4
	v_pk_mul_f32 v[16:17], v[18:19], v[16:17]
	v_pk_mul_f32 v[18:19], v[38:39], v[48:49] op_sel_hi:[1,0]
	v_lshlrev_b32_e32 v4, 16, v5
	v_and_b32_e32 v5, 0xffff0000, v5
	v_pk_mul_f32 v[18:19], v[92:93], v[18:19]
	v_pk_mul_f32 v[28:29], v[104:105], v[28:29]
	v_pk_mul_f32 v[18:19], v[18:19], v[4:5]
	v_lshlrev_b32_e32 v4, 16, v6
	v_and_b32_e32 v5, 0xffff0000, v6
	v_pk_mul_f32 v[28:29], v[28:29], v[4:5]
	v_lshlrev_b32_e32 v4, 16, v7
	v_and_b32_e32 v5, 0xffff0000, v7
	v_pk_mul_f32 v[6:7], v[46:47], v[48:49] op_sel_hi:[1,0]
	s_addc_u32 s5, s5, 0
	v_pk_mul_f32 v[6:7], v[106:107], v[6:7]
	s_add_i32 s15, s15, 32
	v_pk_mul_f32 v[30:31], v[6:7], v[4:5]
	v_cvt_pk_bf16_f32 v5, v8, v9
	v_add_co_u32_e32 v8, vcc, s31, v78
	v_cvt_pk_bf16_f32 v4, v12, v13
	v_cvt_pk_bf16_f32 v6, v14, v15
	v_cvt_pk_bf16_f32 v7, v10, v11
	v_addc_co_u32_e32 v9, vcc, 0, v79, vcc
	global_store_dwordx4 v[8:9], v[4:7], off
	s_cmp_eq_u32 s12, 0x3d0000
	v_lshl_add_u64 v[70:71], v[70:71], 0, s[24:25]
	v_cvt_pk_bf16_f32 v4, v16, v17
	v_cvt_pk_bf16_f32 v5, v18, v19
	v_cvt_pk_bf16_f32 v6, v28, v29
	v_cvt_pk_bf16_f32 v7, v30, v31
	global_store_dwordx4 v[8:9], v[4:7], off offset:16
	s_waitcnt lgkmcnt(0)
	s_barrier
	s_cbranch_scc1 .LBB0_1842
	s_waitcnt vmcnt(3)
	v_mov_b64_e32 v[8:9], v[24:25]
	s_waitcnt vmcnt(2)
	v_mov_b64_e32 v[4:5], v[20:21]
	v_mov_b64_e32 v[48:49], v[64:65]
	v_mov_b64_e32 v[44:45], v[60:61]
	v_mov_b64_e32 v[36:37], v[56:57]
	v_mov_b64_e32 v[28:29], v[52:53]
	v_mov_b64_e32 v[16:17], v[40:41]
	v_mov_b64_e32 v[12:13], v[32:33]
	v_mov_b64_e32 v[10:11], v[26:27]
	v_mov_b64_e32 v[6:7], v[22:23]
	v_mov_b64_e32 v[50:51], v[66:67]
	v_mov_b64_e32 v[46:47], v[62:63]
	v_mov_b64_e32 v[38:39], v[58:59]
	v_mov_b64_e32 v[30:31], v[54:55]
	v_mov_b64_e32 v[18:19], v[42:43]
	v_mov_b64_e32 v[14:15], v[34:35]
	v_mov_b32_e32 v123, v84
	v_mov_b32_e32 v124, v85
	v_mov_b32_e32 v116, v68
	v_mov_b32_e32 v125, v86
	v_mov_b32_e32 v126, v87
	s_branch .LBB0_1838

; #define LAS __attribute__((address_space(3)))
; __device__ __forceinline__ unsigned f2bf(float f) { return pk2(f, f) & 0xffffu; }
; __device__ __forceinline__ int perm16(int e) { return (e & ~12) | ((e >> 1) & 4) | ((e << 1) & 8); }
; __device__ __forceinline__ void delta_rec_stage(LAS unsigned char* buf, int pt, const DeltaPre& dp) {
;     const int tt = pt >> 3, dg = pt & 7, d0 = dg * 16;
;     { LAS bf16* dst = (LAS bf16*)(buf + (pt < 128 ? DR_TI : DR_AT)) + ((pt & 127) >> 2) * 40 + (pt & 3) * 8; *(LAS u32x4*)dst = dp.tia; }
;     if (pt == 0) *(LAS float*)(buf + DR_EGL) = __expf(dp.gl);
;     const float eg = __expf(dp.gct), ekd = __expf(dp.gl - dp.gct);
;     const float fq = dp.nq * eg, fkb = dp.nk * dp.bet * eg, fkd = dp.nk * ekd, bet = dp.bet;
;     float k[16], q[16], v[16];
;     unpack8(dp.k0, k); unpack8(dp.k1, k + 8); unpack8(dp.q0, q); unpack8(dp.q1, q + 8); unpack8(dp.v0, v); unpack8(dp.v1, v + 8);
;     LAS bf16* KB = (LAS bf16*)(buf + DR_KB) + tt * 136 + d0; LAS bf16* QD = (LAS bf16*)(buf + DR_QD) + tt * 136 + d0;
;     *(LAS bf16x8*)KB = pack8(k[0] * fkb, k[1] * fkb, k[2] * fkb, k[3] * fkb, k[8] * fkb, k[9] * fkb, k[10] * fkb, k[11] * fkb);
;     *(LAS bf16x8*)(KB + 8) = pack8(k[4] * fkb, k[5] * fkb, k[6] * fkb, k[7] * fkb, k[12] * fkb, k[13] * fkb, k[14] * fkb, k[15] * fkb);
;     *(LAS bf16x8*)QD = pack8(q[0] * fq, q[1] * fq, q[2] * fq, q[3] * fq, q[8] * fq, q[9] * fq, q[10] * fq, q[11] * fq);
;     *(LAS bf16x8*)(QD + 8) = pack8(q[4] * fq, q[5] * fq, q[6] * fq, q[7] * fq, q[12] * fq, q[13] * fq, q[14] * fq, q[15] * fq);
;     LAS bf16* KDT = (LAS bf16*)(buf + DR_KDT) + d0 * 40 + perm16(tt);
; #pragma unroll
;     for (int e = 0; e < 16; ++e) KDT[e * 40] = (bf16)f2bf(k[e] * fkd);
;     LAS float* VB = (LAS float*)(buf + DR_VB) + tt * 132 + d0;
; #pragma unroll
;     for (int e4 = 0; e4 < 4; ++e4) *(LAS f32x4*)(VB + 4 * e4) = (f32x4){v[4 * e4] * bet, v[4 * e4 + 1] * bet, v[4 * e4 + 2] * bet, v[4 * e4 + 3] * bet};
; }
; __device__ __forceinline__ void delta_out_norm(const LAS float* ob, int pt, const float* dn16, const u32x4 z0, const u32x4 z1, bf16* dst) {
;     const LAS float* p = ob + (pt >> 3) * 132 + (pt & 7) * 16;
;     float o[16], z[16];
; #pragma unroll
;     for (int e4 = 0; e4 < 4; ++e4) { const f32x4 t = *(const LAS f32x4*)(p + 4 * e4); o[4 * e4] = t[0]; o[4 * e4 + 1] = t[1]; o[4 * e4 + 2] = t[2]; o[4 * e4 + 3] = t[3]; }
.LBB0_1844:
	s_or_b64 exec, exec, s[4:5]
	v_mul_f32_e32 v0, 0x3fb8aa3b, v84
	v_sub_f32_e32 v1, v85, v84
	v_exp_f32_e32 v0, v0
	v_mul_f32_e32 v1, 0x3fb8aa3b, v1
	v_exp_f32_e32 v1, v1
	v_mul_f32_e32 v2, v68, v86
	v_mul_f32_e32 v16, v0, v2
	v_lshlrev_b32_e32 v18, 16, v64
	v_and_b32_e32 v19, 0xffff0000, v64
	v_lshlrev_b32_e32 v28, 16, v65
	v_and_b32_e32 v29, 0xffff0000, v65
	v_lshlrev_b32_e32 v30, 16, v60
	v_and_b32_e32 v31, 0xffff0000, v60
	v_lshlrev_b32_e32 v38, 16, v61
	v_and_b32_e32 v39, 0xffff0000, v61
	v_mul_f32_e32 v14, v0, v87
	v_mul_f32_e32 v69, v86, v1
	v_pk_mul_f32 v[0:1], v[16:17], v[18:19] op_sel_hi:[0,1]
	v_pk_mul_f32 v[2:3], v[16:17], v[28:29] op_sel_hi:[0,1]
	v_pk_mul_f32 v[36:37], v[16:17], v[30:31] op_sel_hi:[0,1]
	v_pk_mul_f32 v[44:45], v[16:17], v[38:39] op_sel_hi:[0,1]
	v_add3_u32 v70, s12, v91, v114
	v_cvt_pk_bf16_f32 v0, v0, v1
	v_cvt_pk_bf16_f32 v1, v2, v3
	v_cvt_pk_bf16_f32 v2, v36, v37
	v_cvt_pk_bf16_f32 v3, v44, v45
	v_lshlrev_b32_e32 v36, 16, v66
	v_and_b32_e32 v37, 0xffff0000, v66
	v_lshlrev_b32_e32 v44, 16, v67
	v_and_b32_e32 v45, 0xffff0000, v67
	v_lshlrev_b32_e32 v46, 16, v62
	v_and_b32_e32 v47, 0xffff0000, v62
	v_lshlrev_b32_e32 v50, 16, v63
	v_and_b32_e32 v51, 0xffff0000, v63
	ds_write_b128 v70, v[0:3]
	v_pk_mul_f32 v[0:1], v[16:17], v[36:37] op_sel_hi:[0,1]
	v_pk_mul_f32 v[2:3], v[16:17], v[44:45] op_sel_hi:[0,1]
	v_pk_mul_f32 v[48:49], v[16:17], v[46:47] op_sel_hi:[0,1]
	v_pk_mul_f32 v[16:17], v[16:17], v[50:51] op_sel_hi:[0,1]
	v_cvt_pk_bf16_f32 v0, v0, v1
	v_cvt_pk_bf16_f32 v1, v2, v3
	v_cvt_pk_bf16_f32 v2, v48, v49
	v_cvt_pk_bf16_f32 v3, v16, v17
	ds_write_b128 v70, v[0:3] offset:16
	v_lshlrev_b32_e32 v0, 16, v56
	v_and_b32_e32 v1, 0xffff0000, v56
	v_lshlrev_b32_e32 v2, 16, v57
	v_and_b32_e32 v3, 0xffff0000, v57
	v_lshlrev_b32_e32 v16, 16, v52
	v_and_b32_e32 v17, 0xffff0000, v52
	v_lshlrev_b32_e32 v48, 16, v53
	v_and_b32_e32 v49, 0xffff0000, v53
	v_pk_mul_f32 v[0:1], v[14:15], v[0:1] op_sel_hi:[0,1]
	v_pk_mul_f32 v[2:3], v[14:15], v[2:3] op_sel_hi:[0,1]
	v_pk_mul_f32 v[16:17], v[14:15], v[16:17] op_sel_hi:[0,1]
	v_pk_mul_f32 v[48:49], v[14:15], v[48:49] op_sel_hi:[0,1]
	v_cvt_pk_bf16_f32 v0, v0, v1
	v_cvt_pk_bf16_f32 v1, v2, v3
	v_cvt_pk_bf16_f32 v2, v16, v17
	v_cvt_pk_bf16_f32 v3, v48, v49
	ds_write_b128 v70, v[0:3] offset:8704
	v_lshlrev_b32_e32 v0, 16, v58
	v_and_b32_e32 v1, 0xffff0000, v58
	v_lshlrev_b32_e32 v2, 16, v59
	v_and_b32_e32 v3, 0xffff0000, v59
	v_lshlrev_b32_e32 v16, 16, v54
	v_and_b32_e32 v17, 0xffff0000, v54
	v_lshlrev_b32_e32 v48, 16, v55
	v_and_b32_e32 v49, 0xffff0000, v55
	v_pk_mul_f32 v[0:1], v[14:15], v[0:1] op_sel_hi:[0,1]
	v_pk_mul_f32 v[2:3], v[14:15], v[2:3] op_sel_hi:[0,1]
	v_pk_mul_f32 v[16:17], v[14:15], v[16:17] op_sel_hi:[0,1]
	v_pk_mul_f32 v[14:15], v[14:15], v[48:49] op_sel_hi:[0,1]
	v_cvt_pk_bf16_f32 v0, v0, v1
	v_cvt_pk_bf16_f32 v1, v2, v3
	v_cvt_pk_bf16_f32 v2, v16, v17
	v_cvt_pk_bf16_f32 v3, v14, v15
	ds_write_b128 v70, v[0:3] offset:8720
	v_add3_u32 v0, s12, v90, v80
	v_mul_f32_e32 v1, v69, v18
	v_add3_u32 v0, v0, v81, v82
	v_cvt_pk_bf16_f32 v1, v1, s0
	ds_write_b16 v0, v1 offset:17408
	v_mul_f32_e32 v1, v69, v19
	v_cvt_pk_bf16_f32 v1, v1, s0
	ds_write_b16 v0, v1 offset:18048
	v_mul_f32_e32 v1, v69, v28
	v_cvt_pk_bf16_f32 v1, v1, s0
	ds_write_b16 v0, v1 offset:18688
	v_mul_f32_e32 v1, v69, v29
	v_cvt_pk_bf16_f32 v1, v1, s0
	ds_write_b16 v0, v1 offset:19328
	v_mul_f32_e32 v1, v69, v36
	v_cvt_pk_bf16_f32 v1, v1, s0
	ds_write_b16 v0, v1 offset:19968
	v_mul_f32_e32 v1, v69, v37
	v_cvt_pk_bf16_f32 v1, v1, s0
	ds_write_b16 v0, v1 offset:20608
	v_mul_f32_e32 v1, v69, v44
	v_cvt_pk_bf16_f32 v1, v1, s0
	ds_write_b16 v0, v1 offset:21248
	v_mul_f32_e32 v1, v69, v45
	v_cvt_pk_bf16_f32 v1, v1, s0
	ds_write_b16 v0, v1 offset:21888
	v_mul_f32_e32 v1, v69, v30
	v_cvt_pk_bf16_f32 v1, v1, s0
	ds_write_b16 v0, v1 offset:22528
	v_mul_f32_e32 v1, v69, v31
	v_cvt_pk_bf16_f32 v1, v1, s0
	ds_write_b16 v0, v1 offset:23168
	v_mul_f32_e32 v1, v69, v38
	v_cvt_pk_bf16_f32 v1, v1, s0
	ds_write_b16 v0, v1 offset:23808
	v_mul_f32_e32 v1, v69, v39
	v_cvt_pk_bf16_f32 v1, v1, s0
	ds_write_b16 v0, v1 offset:24448
	v_mul_f32_e32 v1, v69, v46
	v_cvt_pk_bf16_f32 v1, v1, s0
	ds_write_b16 v0, v1 offset:25088
	v_mul_f32_e32 v1, v69, v47
	v_cvt_pk_bf16_f32 v1, v1, s0
	ds_write_b16 v0, v1 offset:25728
	v_mul_f32_e32 v1, v69, v50
	v_cvt_pk_bf16_f32 v1, v1, s0
	ds_write_b16 v0, v1 offset:26368
	v_mul_f32_e32 v1, v69, v51
	v_cvt_pk_bf16_f32 v1, v1, s0
	ds_write_b16 v0, v1 offset:27008
	v_lshlrev_b32_e32 v0, 16, v40
	v_and_b32_e32 v1, 0xffff0000, v40
	v_lshlrev_b32_e32 v2, 16, v41
	v_and_b32_e32 v3, 0xffff0000, v41
	v_add3_u32 v14, s12, v88, v111
	v_pk_mul_f32 v[0:1], v[68:69], v[0:1] op_sel_hi:[0,1]
	v_pk_mul_f32 v[2:3], v[68:69], v[2:3] op_sel_hi:[0,1]
	ds_write_b128 v14, v[0:3] offset:32768
	v_lshlrev_b32_e32 v0, 16, v42
	v_and_b32_e32 v1, 0xffff0000, v42
	v_lshlrev_b32_e32 v2, 16, v43
	v_and_b32_e32 v3, 0xffff0000, v43
	v_pk_mul_f32 v[0:1], v[68:69], v[0:1] op_sel_hi:[0,1]
	v_pk_mul_f32 v[2:3], v[68:69], v[2:3] op_sel_hi:[0,1]
	ds_write_b128 v14, v[0:3] offset:32784
	v_lshlrev_b32_e32 v0, 16, v32
	v_and_b32_e32 v1, 0xffff0000, v32
	v_lshlrev_b32_e32 v2, 16, v33
	v_and_b32_e32 v3, 0xffff0000, v33
	v_pk_mul_f32 v[0:1], v[68:69], v[0:1] op_sel_hi:[0,1]
	v_pk_mul_f32 v[2:3], v[68:69], v[2:3] op_sel_hi:[0,1]
	ds_write_b128 v14, v[0:3] offset:32800
	v_lshlrev_b32_e32 v0, 16, v34
	v_and_b32_e32 v1, 0xffff0000, v34
	v_lshlrev_b32_e32 v2, 16, v35
	v_and_b32_e32 v3, 0xffff0000, v35
	v_pk_mul_f32 v[0:1], v[68:69], v[0:1] op_sel_hi:[0,1]
	v_pk_mul_f32 v[2:3], v[68:69], v[2:3] op_sel_hi:[0,1]
	ds_write_b128 v14, v[0:3] offset:32816
	ds_read_b128 v[0:3], v89 offset:16896
	ds_read_b128 v[14:17], v89 offset:16912
	ds_read_b128 v[28:31], v89 offset:16928
	ds_read_b128 v[32:35], v89 offset:16944
	v_mov_b32_e32 v40, 0x358637bd
	s_waitcnt vmcnt(5)
; #define LAS __attribute__((address_space(3)))
; __device__ __forceinline__ float rsq_f(float x) { return __builtin_amdgcn_rsqf(x); }
; __device__ __forceinline__ float red8(float x) { x += dpp_f<0xB1>(x); x += dpp_f<0x4E>(x); x += dpp_f<0x141>(x); return x; }
; __device__ __forceinline__ void unpack8(const u32x4 u, float* x) { x[0] = bflo(u.x); x[1] = bfhi(u.x); x[2] = bflo(u.y); x[3] = bfhi(u.y); x[4] = bflo(u.z); x[5] = bfhi(u.z); x[6] = bflo(u.w); x[7] = bfhi(u.w); }
; #define DR_BAR() do { asm volatile("s_waitcnt lgkmcnt(0)" ::: "memory"); __builtin_amdgcn_s_barrier(); asm volatile("" ::: "memory"); } while (0)
; __device__ __forceinline__ void delta_out_norm(const LAS float* ob, int pt, const float* dn16, const u32x4 z0, const u32x4 z1, bf16* dst) {
;     const LAS float* p = ob + (pt >> 3) * 132 + (pt & 7) * 16;
;     float o[16], z[16];
; #pragma unroll
;     for (int e4 = 0; e4 < 4; ++e4) { const f32x4 t = *(const LAS f32x4*)(p + 4 * e4); o[4 * e4] = t[0]; o[4 * e4 + 1] = t[1]; o[4 * e4 + 2] = t[2]; o[4 * e4 + 3] = t[3]; }
;     float ss = 0.f;
; #pragma unroll
;     for (int e = 0; e < 16; ++e) ss += o[e] * o[e];
;     ss = red8(ss);
;     const float rstd = rsq_f(ss * (1.f / 128.f) + EPS);
;     unpack8(z0, z); unpack8(z1, z + 8);
; #pragma unroll
;     for (int e = 0; e < 16; ++e) o[e] = o[e] * rstd * dn16[e] * z[e];
;     *(bf16x8*)dst = pack8(o[0], o[1], o[2], o[3], o[4], o[5], o[6], o[7]); *(bf16x8*)(dst + 8) = pack8(o[8], o[9], o[10], o[11], o[12], o[13], o[14], o[15]);
; }
; __device__ __forceinline__ void delta_rec_task(const Params& P, LAS unsigned char* lds, int b, int h, int tid) {
;     ...
;             if (c > 0) delta_out_norm((const LAS float*)(lds + DR_OB) + ((c - 1) & 1) * 32 * 132, pt, dn16, zc0, zc1, zgp + (size_t)(c - 1) * 32 * D);
;             DR_BAR();
;         }
;         delta_out_norm((const LAS float*)(lds + DR_OB) + ((NC - 1) & 1) * 32 * 132, pt, dn16, zn0, zn1, zgp + (size_t)(NC - 1) * 32 * D);
	v_and_b32_e32 v39, 0xffff0000, v24
	s_mov_b64 s[4:5], 0x3d0000
	s_waitcnt lgkmcnt(3)
	v_mul_f32_e32 v36, v1, v1
	v_fmac_f32_e32 v36, v0, v0
	v_fmac_f32_e32 v36, v2, v2
	v_fmac_f32_e32 v36, v3, v3
	s_waitcnt lgkmcnt(2)
	v_fmac_f32_e32 v36, v14, v14
	v_fmac_f32_e32 v36, v15, v15
	v_fmac_f32_e32 v36, v16, v16
	v_fmac_f32_e32 v36, v17, v17
	s_waitcnt lgkmcnt(1)
	v_fmac_f32_e32 v36, v28, v28
	v_fmac_f32_e32 v36, v29, v29
	v_pk_mul_f32 v[18:19], v[30:31], v[30:31]
	s_nop 0
	v_add_f32_e32 v18, v18, v36
	v_add_f32_e32 v38, v19, v18
	s_waitcnt lgkmcnt(0)
	v_pk_mul_f32 v[36:37], v[32:33], v[32:33]
	v_pk_mul_f32 v[18:19], v[34:35], v[34:35]
	v_add_f32_e32 v36, v36, v38
	v_add_f32_e32 v36, v37, v36
	v_add_f32_e32 v18, v18, v36
	v_add_f32_e32 v18, v19, v18
	v_lshlrev_b32_e32 v38, 16, v24
	v_lshlrev_b32_e32 v24, 16, v25
	v_add_f32_dpp v18, v18, v18 quad_perm:[1,0,3,2] row_mask:0xf bank_mask:0xf bound_ctrl:1
	v_and_b32_e32 v25, 0xffff0000, v25
	v_lshl_add_u64 v[36:37], v[108:109], 0, s[4:5]
	v_add_f32_dpp v18, v18, v18 quad_perm:[2,3,0,1] row_mask:0xf bank_mask:0xf bound_ctrl:1
	s_mov_b32 s4, 0x3d0000
	s_nop 0
	v_add_f32_dpp v18, v18, v18 row_half_mirror row_mask:0xf bank_mask:0xf bound_ctrl:1
	v_fmamk_f32 v18, v18, 0x3c000000, v40
	v_rsq_f32_e32 v18, v18
	s_nop 0
	v_pk_mul_f32 v[2:3], v[2:3], v[18:19] op_sel_hi:[1,0]
	s_nop 0
	v_pk_mul_f32 v[2:3], v[100:101], v[2:3]
	v_pk_mul_f32 v[14:15], v[14:15], v[18:19] op_sel_hi:[1,0]
	v_pk_mul_f32 v[2:3], v[2:3], v[24:25]
	v_lshlrev_b32_e32 v24, 16, v26
	v_and_b32_e32 v25, 0xffff0000, v26
	v_pk_mul_f32 v[14:15], v[98:99], v[14:15]
	v_pk_mul_f32 v[16:17], v[16:17], v[18:19] op_sel_hi:[1,0]
	v_pk_mul_f32 v[14:15], v[14:15], v[24:25]
	v_lshlrev_b32_e32 v24, 16, v27
	v_and_b32_e32 v25, 0xffff0000, v27
	v_pk_mul_f32 v[16:17], v[96:97], v[16:17]
	v_pk_mul_f32 v[26:27], v[28:29], v[18:19] op_sel_hi:[1,0]
	v_pk_mul_f32 v[0:1], v[0:1], v[18:19] op_sel_hi:[1,0]
	v_pk_mul_f32 v[16:17], v[16:17], v[24:25]
	s_waitcnt vmcnt(4)
	v_lshlrev_b32_e32 v24, 16, v20
	v_and_b32_e32 v25, 0xffff0000, v20
	v_pk_mul_f32 v[26:27], v[94:95], v[26:27]
	v_pk_mul_f32 v[0:1], v[102:103], v[0:1]
	v_pk_mul_f32 v[24:25], v[26:27], v[24:25]
	v_pk_mul_f32 v[26:27], v[30:31], v[18:19] op_sel_hi:[1,0]
	v_pk_mul_f32 v[0:1], v[0:1], v[38:39]
	v_lshlrev_b32_e32 v20, 16, v21
	v_and_b32_e32 v21, 0xffff0000, v21
	v_pk_mul_f32 v[26:27], v[92:93], v[26:27]
	v_pk_mul_f32 v[28:29], v[32:33], v[18:19] op_sel_hi:[1,0]
	v_pk_mul_f32 v[18:19], v[34:35], v[18:19] op_sel_hi:[1,0]
	v_pk_mul_f32 v[20:21], v[26:27], v[20:21]
	v_lshlrev_b32_e32 v26, 16, v22
	v_and_b32_e32 v27, 0xffff0000, v22
	v_pk_mul_f32 v[28:29], v[104:105], v[28:29]
	v_lshlrev_b32_e32 v22, 16, v23
	v_and_b32_e32 v23, 0xffff0000, v23
	v_pk_mul_f32 v[18:19], v[106:107], v[18:19]
	v_cvt_pk_bf16_f32 v0, v0, v1
	v_cvt_pk_bf16_f32 v1, v2, v3
	v_cvt_pk_bf16_f32 v2, v14, v15
	v_add_co_u32_e32 v14, vcc, s4, v108
	v_pk_mul_f32 v[26:27], v[28:29], v[26:27]
	v_pk_mul_f32 v[18:19], v[18:19], v[22:23]
	v_cvt_pk_bf16_f32 v3, v16, v17
	v_addc_co_u32_e32 v15, vcc, 0, v109, vcc
	global_store_dwordx4 v[14:15], v[0:3], off
	s_mov_b64 s[4:5], 0x3f0000
	v_lshl_add_u64 v[34:35], v[108:109], 0, s[4:5]
	v_cvt_pk_bf16_f32 v0, v24, v25
	v_cvt_pk_bf16_f32 v1, v20, v21
	v_cvt_pk_bf16_f32 v2, v26, v27
	v_cvt_pk_bf16_f32 v3, v18, v19
	global_store_dwordx4 v[36:37], v[0:3], off offset:16
	s_waitcnt lgkmcnt(0)
	s_barrier
	ds_read_b128 v[0:3], v89
	ds_read_b128 v[14:17], v89 offset:16
	ds_read_b128 v[18:21], v89 offset:32
	ds_read_b128 v[22:25], v89 offset:48
	s_mov_b32 s4, 0x3f0000
	v_add_co_u32_e32 v36, vcc, s4, v108
	s_waitcnt lgkmcnt(3)
	v_mul_f32_e32 v28, v1, v1
	v_fmac_f32_e32 v28, v0, v0
	v_fmac_f32_e32 v28, v2, v2
	v_fmac_f32_e32 v28, v3, v3
	s_waitcnt lgkmcnt(2)
	v_fmac_f32_e32 v28, v14, v14
	v_fmac_f32_e32 v28, v15, v15
	v_fmac_f32_e32 v28, v16, v16
	v_fmac_f32_e32 v28, v17, v17
	s_waitcnt lgkmcnt(1)
	v_fmac_f32_e32 v28, v18, v18
	v_fmac_f32_e32 v28, v19, v19
	v_pk_mul_f32 v[26:27], v[20:21], v[20:21]
	v_addc_co_u32_e32 v37, vcc, 0, v109, vcc
	v_add_f32_e32 v26, v26, v28
	v_add_f32_e32 v30, v27, v26
	s_waitcnt lgkmcnt(0)
	v_pk_mul_f32 v[28:29], v[22:23], v[22:23]
	v_pk_mul_f32 v[26:27], v[24:25], v[24:25]
	v_add_f32_e32 v28, v28, v30
	v_add_f32_e32 v28, v29, v28
	v_add_f32_e32 v26, v26, v28
	v_add_f32_e32 v26, v27, v26
	s_nop 1
	v_add_f32_dpp v26, v26, v26 quad_perm:[1,0,3,2] row_mask:0xf bank_mask:0xf bound_ctrl:1
	s_nop 1
	v_add_f32_dpp v26, v26, v26 quad_perm:[2,3,0,1] row_mask:0xf bank_mask:0xf bound_ctrl:1
	s_nop 1
	v_add_f32_dpp v26, v26, v26 row_half_mirror row_mask:0xf bank_mask:0xf bound_ctrl:1
	v_fmamk_f32 v26, v26, 0x3c000000, v40
	v_rsq_f32_e32 v38, v26
	global_load_dwordx4 v[26:29], v[36:37], off
	global_load_dwordx4 v[30:33], v[34:35], off offset:16
	s_waitcnt vmcnt(5)
	v_lshlrev_b32_e32 v34, 16, v8
	v_and_b32_e32 v35, 0xffff0000, v8
	v_pk_mul_f32 v[2:3], v[2:3], v[38:39] op_sel_hi:[1,0]
	v_lshlrev_b32_e32 v8, 16, v9
	v_and_b32_e32 v9, 0xffff0000, v9
	v_pk_mul_f32 v[2:3], v[100:101], v[2:3]
	v_pk_mul_f32 v[14:15], v[14:15], v[38:39] op_sel_hi:[1,0]
	v_pk_mul_f32 v[2:3], v[2:3], v[8:9]
	v_lshlrev_b32_e32 v8, 16, v10
	v_and_b32_e32 v9, 0xffff0000, v10
	v_pk_mul_f32 v[14:15], v[98:99], v[14:15]
	v_lshlrev_b32_e32 v10, 16, v11
	v_pk_mul_f32 v[8:9], v[14:15], v[8:9]
	v_pk_mul_f32 v[14:15], v[16:17], v[38:39] op_sel_hi:[1,0]
	v_and_b32_e32 v11, 0xffff0000, v11
	v_pk_mul_f32 v[14:15], v[96:97], v[14:15]
	v_pk_mul_f32 v[16:17], v[18:19], v[38:39] op_sel_hi:[1,0]
	v_pk_mul_f32 v[10:11], v[14:15], v[10:11]
	s_waitcnt vmcnt(4)
	v_lshlrev_b32_e32 v14, 16, v4
	v_and_b32_e32 v15, 0xffff0000, v4
	v_pk_mul_f32 v[16:17], v[94:95], v[16:17]
	v_pk_mul_f32 v[0:1], v[0:1], v[38:39] op_sel_hi:[1,0]
	v_pk_mul_f32 v[14:15], v[16:17], v[14:15]
	v_pk_mul_f32 v[16:17], v[20:21], v[38:39] op_sel_hi:[1,0]
	v_lshlrev_b32_e32 v4, 16, v5
	v_and_b32_e32 v5, 0xffff0000, v5
	v_pk_mul_f32 v[16:17], v[92:93], v[16:17]
	v_pk_mul_f32 v[18:19], v[22:23], v[38:39] op_sel_hi:[1,0]
	v_pk_mul_f32 v[0:1], v[102:103], v[0:1]
	v_pk_mul_f32 v[4:5], v[16:17], v[4:5]
	v_lshlrev_b32_e32 v16, 16, v6
	v_and_b32_e32 v17, 0xffff0000, v6
	v_pk_mul_f32 v[18:19], v[104:105], v[18:19]
	v_pk_mul_f32 v[0:1], v[0:1], v[34:35]
	v_pk_mul_f32 v[16:17], v[18:19], v[16:17]
	v_pk_mul_f32 v[18:19], v[24:25], v[38:39] op_sel_hi:[1,0]
	v_lshlrev_b32_e32 v6, 16, v7
	v_and_b32_e32 v7, 0xffff0000, v7
	v_pk_mul_f32 v[18:19], v[106:107], v[18:19]
	v_cvt_pk_bf16_f32 v0, v0, v1
	v_cvt_pk_bf16_f32 v1, v2, v3
	v_cvt_pk_bf16_f32 v2, v8, v9
	v_cvt_pk_bf16_f32 v3, v10, v11
	v_pk_mul_f32 v[6:7], v[18:19], v[6:7]
	global_store_dwordx4 v[12:13], v[0:3], off
	s_nop 1
	v_cvt_pk_bf16_f32 v1, v4, v5
	v_add_co_u32_e32 v4, vcc, s3, v108
	v_cvt_pk_bf16_f32 v0, v14, v15
	v_cvt_pk_bf16_f32 v2, v16, v17
	v_cvt_pk_bf16_f32 v3, v6, v7
	v_addc_co_u32_e32 v5, vcc, 0, v109, vcc
	global_store_dwordx4 v[4:5], v[0:3], off offset:16
	s_add_i32 s3, 0, 0x1c620
	s_waitcnt lgkmcnt(0)
	s_barrier
; #define LAS __attribute__((address_space(3)))
; __device__ __forceinline__ float rsq_f(float x) { return __builtin_amdgcn_rsqf(x); }
; __device__ __forceinline__ float red8(float x) { x += dpp_f<0xB1>(x); x += dpp_f<0x4E>(x); x += dpp_f<0x141>(x); return x; }
; __device__ __forceinline__ void unpack8(const u32x4 u, float* x) { x[0] = bflo(u.x); x[1] = bfhi(u.x); x[2] = bflo(u.y); x[3] = bfhi(u.y); x[4] = bflo(u.z); x[5] = bfhi(u.z); x[6] = bflo(u.w); x[7] = bfhi(u.w); }
; __device__ __forceinline__ void delta_out_norm(const LAS float* ob, int pt, const float* dn16, const u32x4 z0, const u32x4 z1, bf16* dst) {
;     const LAS float* p = ob + (pt >> 3) * 132 + (pt & 7) * 16;
;     float o[16], z[16];
; #pragma unroll
;     for (int e4 = 0; e4 < 4; ++e4) { const f32x4 t = *(const LAS f32x4*)(p + 4 * e4); o[4 * e4] = t[0]; o[4 * e4 + 1] = t[1]; o[4 * e4 + 2] = t[2]; o[4 * e4 + 3] = t[3]; }
;     float ss = 0.f;
; #pragma unroll
;     for (int e = 0; e < 16; ++e) ss += o[e] * o[e];
;     ss = red8(ss);
;     const float rstd = rsq_f(ss * (1.f / 128.f) + EPS);
;     unpack8(z0, z); unpack8(z1, z + 8);
; #pragma unroll
;     for (int e = 0; e < 16; ++e) o[e] = o[e] * rstd * dn16[e] * z[e];
;     *(bf16x8*)dst = pack8(o[0], o[1], o[2], o[3], o[4], o[5], o[6], o[7]); *(bf16x8*)(dst + 8) = pack8(o[8], o[9], o[10], o[11], o[12], o[13], o[14], o[15]);
; }
; __device__ __forceinline__ void delta_rec_task(const Params& P, LAS unsigned char* lds, int b, int h, int tid) {
;     ...
;         delta_out_norm((const LAS float*)(lds + DR_OB) + ((NC - 1) & 1) * 32 * 132, pt, dn16, zn0, zn1, zgp + (size_t)(NC - 1) * 32 * D);
	v_add3_u32 v12, s3, v88, v111
	ds_read_b128 v[0:3], v12
	ds_read_b128 v[4:7], v12 offset:16
	ds_read_b128 v[8:11], v12 offset:32
	ds_read_b128 v[12:15], v12 offset:48
	s_waitcnt lgkmcnt(3)
	v_mul_f32_e32 v18, v1, v1
	v_fmac_f32_e32 v18, v0, v0
	v_fmac_f32_e32 v18, v2, v2
	v_fmac_f32_e32 v18, v3, v3
	s_waitcnt lgkmcnt(2)
	v_fmac_f32_e32 v18, v4, v4
	v_fmac_f32_e32 v18, v5, v5
	v_fmac_f32_e32 v18, v6, v6
	v_fmac_f32_e32 v18, v7, v7
	s_waitcnt lgkmcnt(1)
	v_fmac_f32_e32 v18, v8, v8
	v_fmac_f32_e32 v18, v9, v9
	v_pk_mul_f32 v[16:17], v[10:11], v[10:11]
	s_nop 0
	v_add_f32_e32 v16, v16, v18
	v_add_f32_e32 v20, v17, v16
	s_waitcnt lgkmcnt(0)
	v_pk_mul_f32 v[18:19], v[12:13], v[12:13]
	v_pk_mul_f32 v[16:17], v[14:15], v[14:15]
	v_add_f32_e32 v18, v18, v20
	v_add_f32_e32 v18, v19, v18
	v_add_f32_e32 v16, v16, v18
	v_add_f32_e32 v16, v17, v16
	s_waitcnt vmcnt(3)
	v_lshlrev_b32_e32 v18, 16, v26
	v_and_b32_e32 v19, 0xffff0000, v26
	v_add_f32_dpp v16, v16, v16 quad_perm:[1,0,3,2] row_mask:0xf bank_mask:0xf bound_ctrl:1
	s_nop 1
	v_add_f32_dpp v16, v16, v16 quad_perm:[2,3,0,1] row_mask:0xf bank_mask:0xf bound_ctrl:1
	s_nop 1
	v_add_f32_dpp v16, v16, v16 row_half_mirror row_mask:0xf bank_mask:0xf bound_ctrl:1
	v_fmac_f32_e32 v40, 0x3c000000, v16
	v_rsq_f32_e32 v16, v40
	s_nop 0
	v_pk_mul_f32 v[0:1], v[0:1], v[16:17] op_sel_hi:[1,0]
	s_nop 0
	v_pk_mul_f32 v[0:1], v[102:103], v[0:1]
	v_pk_mul_f32 v[2:3], v[2:3], v[16:17] op_sel_hi:[1,0]
	v_pk_mul_f32 v[0:1], v[0:1], v[18:19]
	v_lshlrev_b32_e32 v18, 16, v27
	v_and_b32_e32 v19, 0xffff0000, v27
	v_pk_mul_f32 v[2:3], v[100:101], v[2:3]
	v_pk_mul_f32 v[4:5], v[4:5], v[16:17] op_sel_hi:[1,0]
	v_pk_mul_f32 v[2:3], v[2:3], v[18:19]
	v_lshlrev_b32_e32 v18, 16, v28
	v_and_b32_e32 v19, 0xffff0000, v28
	v_pk_mul_f32 v[4:5], v[98:99], v[4:5]
	v_pk_mul_f32 v[6:7], v[6:7], v[16:17] op_sel_hi:[1,0]
	v_pk_mul_f32 v[4:5], v[4:5], v[18:19]
	v_lshlrev_b32_e32 v18, 16, v29
	v_and_b32_e32 v19, 0xffff0000, v29
	v_pk_mul_f32 v[6:7], v[96:97], v[6:7]
	v_pk_mul_f32 v[8:9], v[8:9], v[16:17] op_sel_hi:[1,0]
	v_pk_mul_f32 v[6:7], v[6:7], v[18:19]
	s_waitcnt vmcnt(2)
	v_lshlrev_b32_e32 v18, 16, v30
	v_and_b32_e32 v19, 0xffff0000, v30
	v_pk_mul_f32 v[8:9], v[94:95], v[8:9]
	v_pk_mul_f32 v[10:11], v[10:11], v[16:17] op_sel_hi:[1,0]
	v_pk_mul_f32 v[8:9], v[8:9], v[18:19]
	v_lshlrev_b32_e32 v18, 16, v31
	v_and_b32_e32 v19, 0xffff0000, v31
	v_pk_mul_f32 v[10:11], v[92:93], v[10:11]
	v_pk_mul_f32 v[12:13], v[12:13], v[16:17] op_sel_hi:[1,0]
	v_pk_mul_f32 v[10:11], v[10:11], v[18:19]
	v_lshlrev_b32_e32 v18, 16, v32
	v_and_b32_e32 v19, 0xffff0000, v32
	v_pk_mul_f32 v[12:13], v[104:105], v[12:13]
	v_pk_mul_f32 v[14:15], v[14:15], v[16:17] op_sel_hi:[1,0]
	v_pk_mul_f32 v[12:13], v[12:13], v[18:19]
	v_lshlrev_b32_e32 v18, 16, v33
	v_and_b32_e32 v19, 0xffff0000, v33
	v_pk_mul_f32 v[14:15], v[106:107], v[14:15]
	v_cvt_pk_bf16_f32 v0, v0, v1
	v_pk_mul_f32 v[14:15], v[14:15], v[18:19]
	v_cvt_pk_bf16_f32 v1, v2, v3
	v_cvt_pk_bf16_f32 v2, v4, v5
	v_cvt_pk_bf16_f32 v3, v6, v7
	global_store_dwordx4 v[36:37], v[0:3], off
	s_nop 1
	v_cvt_pk_bf16_f32 v0, v8, v9
	v_cvt_pk_bf16_f32 v1, v10, v11
	v_cvt_pk_bf16_f32 v2, v12, v13
	v_cvt_pk_bf16_f32 v3, v14, v15
	v_mov_b32_e32 v15, 0
	global_store_dwordx4 v[36:37], v[0:3], off offset:16
	v_mov_b32_e32 v14, v15
	v_mov_b32_e32 v13, v15
	v_mov_b32_e32 v12, v15
	v_mov_b32_e32 v11, v15
	v_mov_b32_e32 v10, v15
	v_mov_b32_e32 v9, v15
	v_mov_b32_e32 v8, v15
	v_mov_b32_e32 v7, v15
	v_mov_b32_e32 v6, v15
	v_mov_b32_e32 v5, v15
	v_mov_b32_e32 v4, v15
	v_mov_b32_e32 v3, v15
	v_mov_b32_e32 v2, v15
	v_mov_b32_e32 v1, v15
	v_mov_b32_e32 v0, v15
	v_mov_b32_e32 v31, v15
	v_mov_b32_e32 v30, v15
	v_mov_b32_e32 v29, v15
	v_mov_b32_e32 v28, v15
	v_mov_b32_e32 v27, v15
	v_mov_b32_e32 v26, v15
	v_mov_b32_e32 v25, v15
	v_mov_b32_e32 v24, v15
	v_mov_b32_e32 v23, v15
	v_mov_b32_e32 v22, v15
	v_mov_b32_e32 v21, v15
	v_mov_b32_e32 v20, v15
	v_mov_b32_e32 v19, v15
	v_mov_b32_e32 v18, v15
	v_mov_b32_e32 v17, v15
	v_mov_b32_e32 v16, v15
	v_mov_b32_e32 v47, v15
	v_mov_b32_e32 v46, v15
	v_mov_b32_e32 v45, v15
	v_mov_b32_e32 v44, v15
	v_mov_b32_e32 v43, v15
	v_mov_b32_e32 v42, v15
	v_mov_b32_e32 v41, v15
	v_mov_b32_e32 v40, v15
	v_mov_b32_e32 v39, v15
	v_mov_b32_e32 v38, v15
	v_mov_b32_e32 v37, v15
	v_mov_b32_e32 v36, v15
	v_mov_b32_e32 v35, v15
	v_mov_b32_e32 v34, v15
	v_mov_b32_e32 v33, v15
	v_mov_b32_e32 v32, v15
	v_mov_b32_e32 v63, v15
	v_mov_b32_e32 v62, v15
	v_mov_b32_e32 v61, v15
	v_mov_b32_e32 v60, v15
	v_mov_b32_e32 v59, v15
	v_mov_b32_e32 v58, v15
	v_mov_b32_e32 v57, v15
	v_mov_b32_e32 v56, v15
	v_mov_b32_e32 v55, v15
	v_mov_b32_e32 v54, v15
	v_mov_b32_e32 v53, v15
	v_mov_b32_e32 v52, v15
	v_mov_b32_e32 v51, v15
	v_mov_b32_e32 v50, v15
	v_mov_b32_e32 v49, v15
	v_mov_b32_e32 v48, v15
	s_or_b64 exec, exec, s[6:7]
	s_and_saveexec_b64 s[4:5], s[8:9]
	s_cbranch_execnz .LBB0_1819
	s_branch .LBB0_1820
